# v6 + already-satisfied s_waitcnt lgkmcnt(N) removed from the MFMA clusters of the 9 bf16 K-loops
# baseline (speedup 1.0000x reference)
.LBB0_156:
	v_add_u32_e32 v139, 0x10000, v137
	ds_read_b128 v[140:143], v139
	ds_read_b128 v[144:147], v139 offset:1024
	ds_read_b128 v[148:151], v139 offset:2048
	ds_read_b128 v[152:155], v139 offset:3072
	v_add_u32_e32 v139, 0x14000, v137
	ds_read_b128 v[156:159], v139
	ds_read_b128 v[160:163], v139 offset:1024
	ds_read_b128 v[164:167], v139 offset:2048
	ds_read_b128 v[168:171], v139 offset:3072
	s_add_u32 s0, s52, 0x100
	s_addc_u32 s1, s53, 0
	s_cmp_eq_u32 s89, 12
	s_cselect_b32 s34, s15, s0
	s_cselect_b32 s35, s14, s1
	s_cselect_b32 s56, s41, s87
	s_cselect_b32 s57, s11, s88
	s_add_u32 s54, s34, 0x80
	s_addc_u32 s55, s35, 0
	ds_read_b128 v[172:175], v138
	ds_read_b128 v[176:179], v138 offset:1024
	ds_read_b128 v[180:183], v138 offset:2048
	ds_read_b128 v[184:187], v138 offset:3072
	ds_read_b128 v[188:191], v138 offset:4096
	ds_read_b128 v[192:195], v138 offset:5120
	ds_read_b128 v[196:199], v138 offset:6144
	ds_read_b128 v[200:203], v138 offset:7168
	s_add_u32 s90, s52, 0x40080
	s_addc_u32 s91, s53, 0
	s_mov_b32 s12, m0
	s_mov_b32 m0, s83
	s_nop 4
	global_load_lds_dwordx4 v1, s[90:91]
	s_mov_b32 m0, s12
	s_add_u32 s52, s52, 0x60080
	s_addc_u32 s53, s53, 0
	s_add_i32 s12, s51, 0xe000
	s_mov_b32 s13, m0
	s_mov_b32 m0, s12
	s_nop 4
	global_load_lds_dwordx4 v1, s[52:53]
	s_mov_b32 m0, s13
	s_waitcnt vmcnt(8)
	s_waitcnt lgkmcnt(0)
	s_barrier
	v_mfma_f32_16x16x32_bf16 v[122:125], v[140:143], v[172:175], v[122:125]
	v_mfma_f32_16x16x32_bf16 v[114:117], v[148:151], v[172:175], v[114:117]
	v_mfma_f32_16x16x32_bf16 v[106:109], v[140:143], v[180:183], v[106:109]
	v_mfma_f32_16x16x32_bf16 v[98:101], v[148:151], v[180:183], v[98:101]
	v_mfma_f32_16x16x32_bf16 v[90:93], v[140:143], v[188:191], v[90:93]
	v_mfma_f32_16x16x32_bf16 v[82:85], v[148:151], v[188:191], v[82:85]
	v_mfma_f32_16x16x32_bf16 v[74:77], v[140:143], v[196:199], v[74:77]
	v_mfma_f32_16x16x32_bf16 v[66:69], v[148:151], v[196:199], v[66:69]
	v_mfma_f32_16x16x32_bf16 v[122:125], v[144:147], v[176:179], v[122:125]
	v_mfma_f32_16x16x32_bf16 v[114:117], v[152:155], v[176:179], v[114:117]
	v_mfma_f32_16x16x32_bf16 v[106:109], v[144:147], v[184:187], v[106:109]
	v_mfma_f32_16x16x32_bf16 v[98:101], v[152:155], v[184:187], v[98:101]
	v_mfma_f32_16x16x32_bf16 v[90:93], v[144:147], v[192:195], v[90:93]
	v_mfma_f32_16x16x32_bf16 v[82:85], v[152:155], v[192:195], v[82:85]
	v_mfma_f32_16x16x32_bf16 v[74:77], v[144:147], v[200:203], v[74:77]
	v_mfma_f32_16x16x32_bf16 v[66:69], v[152:155], v[200:203], v[66:69]
	v_mfma_f32_16x16x32_bf16 v[126:129], v[156:159], v[172:175], v[126:129]
	v_mfma_f32_16x16x32_bf16 v[118:121], v[164:167], v[172:175], v[118:121]
	v_mfma_f32_16x16x32_bf16 v[110:113], v[156:159], v[180:183], v[110:113]
	v_mfma_f32_16x16x32_bf16 v[102:105], v[164:167], v[180:183], v[102:105]
	v_mfma_f32_16x16x32_bf16 v[94:97], v[156:159], v[188:191], v[94:97]
	v_mfma_f32_16x16x32_bf16 v[86:89], v[164:167], v[188:191], v[86:89]
	v_mfma_f32_16x16x32_bf16 v[78:81], v[156:159], v[196:199], v[78:81]
	v_mfma_f32_16x16x32_bf16 v[70:73], v[164:167], v[196:199], v[70:73]
	v_mfma_f32_16x16x32_bf16 v[126:129], v[160:163], v[176:179], v[126:129]
	v_mfma_f32_16x16x32_bf16 v[118:121], v[168:171], v[176:179], v[118:121]
	v_mfma_f32_16x16x32_bf16 v[110:113], v[160:163], v[184:187], v[110:113]
	v_mfma_f32_16x16x32_bf16 v[102:105], v[168:171], v[184:187], v[102:105]
	v_mfma_f32_16x16x32_bf16 v[94:97], v[160:163], v[192:195], v[94:97]
	v_mfma_f32_16x16x32_bf16 v[86:89], v[168:171], v[192:195], v[86:89]
	v_mfma_f32_16x16x32_bf16 v[78:81], v[160:163], v[200:203], v[78:81]
	v_mfma_f32_16x16x32_bf16 v[70:73], v[168:171], v[200:203], v[70:73]
	s_barrier
	s_add_u32 s52, s56, 0x20000
	ds_read_b128 v[172:175], v138 offset:16384
	ds_read_b128 v[176:179], v138 offset:17408
	ds_read_b128 v[180:183], v138 offset:18432
	ds_read_b128 v[184:187], v138 offset:19456
	ds_read_b128 v[188:191], v138 offset:20480
	ds_read_b128 v[192:195], v138 offset:21504
	ds_read_b128 v[196:199], v138 offset:22528
	ds_read_b128 v[200:203], v138 offset:23552
	s_mov_b32 s12, m0
	s_mov_b32 m0, s62
	s_nop 4
	global_load_lds_dwordx4 v134, s[56:57]
	s_mov_b32 m0, s12
	s_addc_u32 s53, s57, 0
	s_mov_b32 s12, m0
	s_mov_b32 m0, s63
	s_nop 4
	global_load_lds_dwordx4 v134, s[52:53]
	s_mov_b32 m0, s12
	s_add_u32 s52, s56, 0x40000
	s_addc_u32 s53, s57, 0
	s_mov_b32 s12, m0
	s_mov_b32 m0, s64
	s_nop 4
	global_load_lds_dwordx4 v134, s[52:53]
	s_mov_b32 m0, s12
	s_add_u32 s52, s56, 0x60000
	s_addc_u32 s53, s57, 0
	s_mov_b32 s12, m0
	s_mov_b32 m0, s65
	s_nop 4
	global_load_lds_dwordx4 v134, s[52:53]
	s_mov_b32 m0, s12
	s_add_u32 s52, s34, 0x20000
	s_mov_b32 s12, m0
	s_mov_b32 m0, s51
	s_nop 4
	global_load_lds_dwordx4 v1, s[34:35]
	s_mov_b32 m0, s12
	s_addc_u32 s53, s35, 0
	s_mov_b32 s12, m0
	s_mov_b32 m0, s73
	s_nop 4
	global_load_lds_dwordx4 v1, s[52:53]
	s_mov_b32 m0, s12
	s_waitcnt vmcnt(8)
	s_waitcnt lgkmcnt(0)
	s_barrier
	v_mfma_f32_16x16x32_bf16 v[58:61], v[140:143], v[172:175], v[58:61]
	v_mfma_f32_16x16x32_bf16 v[50:53], v[148:151], v[172:175], v[50:53]
	v_mfma_f32_16x16x32_bf16 v[42:45], v[140:143], v[180:183], v[42:45]
	v_mfma_f32_16x16x32_bf16 v[34:37], v[148:151], v[180:183], v[34:37]
	v_mfma_f32_16x16x32_bf16 v[26:29], v[140:143], v[188:191], v[26:29]
	v_mfma_f32_16x16x32_bf16 v[18:21], v[148:151], v[188:191], v[18:21]
	v_mfma_f32_16x16x32_bf16 v[10:13], v[140:143], v[196:199], v[10:13]
	v_mfma_f32_16x16x32_bf16 v[2:5], v[148:151], v[196:199], v[2:5]
	v_mfma_f32_16x16x32_bf16 v[58:61], v[144:147], v[176:179], v[58:61]
	v_mfma_f32_16x16x32_bf16 v[50:53], v[152:155], v[176:179], v[50:53]
	v_mfma_f32_16x16x32_bf16 v[42:45], v[144:147], v[184:187], v[42:45]
	v_mfma_f32_16x16x32_bf16 v[34:37], v[152:155], v[184:187], v[34:37]
	v_mfma_f32_16x16x32_bf16 v[26:29], v[144:147], v[192:195], v[26:29]
	v_mfma_f32_16x16x32_bf16 v[18:21], v[152:155], v[192:195], v[18:21]
	v_mfma_f32_16x16x32_bf16 v[10:13], v[144:147], v[200:203], v[10:13]
	v_mfma_f32_16x16x32_bf16 v[2:5], v[152:155], v[200:203], v[2:5]
	v_mfma_f32_16x16x32_bf16 v[62:65], v[156:159], v[172:175], v[62:65]
	v_mfma_f32_16x16x32_bf16 v[54:57], v[164:167], v[172:175], v[54:57]
	v_mfma_f32_16x16x32_bf16 v[46:49], v[156:159], v[180:183], v[46:49]
	v_mfma_f32_16x16x32_bf16 v[38:41], v[164:167], v[180:183], v[38:41]
	v_mfma_f32_16x16x32_bf16 v[30:33], v[156:159], v[188:191], v[30:33]
	v_mfma_f32_16x16x32_bf16 v[22:25], v[164:167], v[188:191], v[22:25]
	v_mfma_f32_16x16x32_bf16 v[14:17], v[156:159], v[196:199], v[14:17]
	v_mfma_f32_16x16x32_bf16 v[6:9], v[164:167], v[196:199], v[6:9]
	v_mfma_f32_16x16x32_bf16 v[62:65], v[160:163], v[176:179], v[62:65]
	v_mfma_f32_16x16x32_bf16 v[54:57], v[168:171], v[176:179], v[54:57]
	v_mfma_f32_16x16x32_bf16 v[46:49], v[160:163], v[184:187], v[46:49]
	v_mfma_f32_16x16x32_bf16 v[38:41], v[168:171], v[184:187], v[38:41]
	v_mfma_f32_16x16x32_bf16 v[30:33], v[160:163], v[192:195], v[30:33]
	v_mfma_f32_16x16x32_bf16 v[22:25], v[168:171], v[192:195], v[22:25]
	v_mfma_f32_16x16x32_bf16 v[14:17], v[160:163], v[200:203], v[14:17]
	v_mfma_f32_16x16x32_bf16 v[6:9], v[168:171], v[200:203], v[6:9]
	s_barrier
	v_add_u32_e32 v139, 0x18000, v137
	ds_read_b128 v[140:143], v139
	ds_read_b128 v[144:147], v139 offset:1024
	ds_read_b128 v[148:151], v139 offset:2048
	ds_read_b128 v[152:155], v139 offset:3072
	v_add_u32_e32 v139, 0x1c000, v137
	ds_read_b128 v[156:159], v139
	ds_read_b128 v[160:163], v139 offset:1024
	ds_read_b128 v[164:167], v139 offset:2048
	ds_read_b128 v[168:171], v139 offset:3072
	ds_read_b128 v[172:175], v138 offset:32768
	ds_read_b128 v[176:179], v138 offset:33792
	ds_read_b128 v[180:183], v138 offset:34816
	ds_read_b128 v[184:187], v138 offset:35840
	ds_read_b128 v[188:191], v138 offset:36864
	ds_read_b128 v[192:195], v138 offset:37888
	ds_read_b128 v[196:199], v138 offset:38912
	ds_read_b128 v[200:203], v138 offset:39936
	s_add_u32 s52, s34, 0x40000
	s_addc_u32 s53, s35, 0
	s_mov_b32 s12, m0
	s_mov_b32 m0, s74
	s_nop 4
	global_load_lds_dwordx4 v1, s[52:53]
	s_mov_b32 m0, s12
	s_add_u32 s52, s34, 0x60000
	s_addc_u32 s53, s35, 0
	s_mov_b32 s12, m0
	s_mov_b32 m0, s75
	s_nop 4
	global_load_lds_dwordx4 v1, s[52:53]
	s_mov_b32 m0, s12
	s_waitcnt vmcnt(8)
	s_waitcnt lgkmcnt(0)
	s_barrier
	v_mfma_f32_16x16x32_bf16 v[122:125], v[140:143], v[172:175], v[122:125]
	v_mfma_f32_16x16x32_bf16 v[114:117], v[148:151], v[172:175], v[114:117]
	v_mfma_f32_16x16x32_bf16 v[106:109], v[140:143], v[180:183], v[106:109]
	v_mfma_f32_16x16x32_bf16 v[98:101], v[148:151], v[180:183], v[98:101]
	v_mfma_f32_16x16x32_bf16 v[90:93], v[140:143], v[188:191], v[90:93]
	v_mfma_f32_16x16x32_bf16 v[82:85], v[148:151], v[188:191], v[82:85]
	v_mfma_f32_16x16x32_bf16 v[74:77], v[140:143], v[196:199], v[74:77]
	v_mfma_f32_16x16x32_bf16 v[66:69], v[148:151], v[196:199], v[66:69]
	v_mfma_f32_16x16x32_bf16 v[122:125], v[144:147], v[176:179], v[122:125]
	v_mfma_f32_16x16x32_bf16 v[114:117], v[152:155], v[176:179], v[114:117]
	v_mfma_f32_16x16x32_bf16 v[106:109], v[144:147], v[184:187], v[106:109]
	v_mfma_f32_16x16x32_bf16 v[98:101], v[152:155], v[184:187], v[98:101]
	v_mfma_f32_16x16x32_bf16 v[90:93], v[144:147], v[192:195], v[90:93]
	v_mfma_f32_16x16x32_bf16 v[82:85], v[152:155], v[192:195], v[82:85]
	v_mfma_f32_16x16x32_bf16 v[74:77], v[144:147], v[200:203], v[74:77]
	v_mfma_f32_16x16x32_bf16 v[66:69], v[152:155], v[200:203], v[66:69]
	v_mfma_f32_16x16x32_bf16 v[126:129], v[156:159], v[172:175], v[126:129]
	v_mfma_f32_16x16x32_bf16 v[118:121], v[164:167], v[172:175], v[118:121]
	v_mfma_f32_16x16x32_bf16 v[110:113], v[156:159], v[180:183], v[110:113]
	v_mfma_f32_16x16x32_bf16 v[102:105], v[164:167], v[180:183], v[102:105]
	v_mfma_f32_16x16x32_bf16 v[94:97], v[156:159], v[188:191], v[94:97]
	v_mfma_f32_16x16x32_bf16 v[86:89], v[164:167], v[188:191], v[86:89]
	v_mfma_f32_16x16x32_bf16 v[78:81], v[156:159], v[196:199], v[78:81]
	v_mfma_f32_16x16x32_bf16 v[70:73], v[164:167], v[196:199], v[70:73]
	v_mfma_f32_16x16x32_bf16 v[126:129], v[160:163], v[176:179], v[126:129]
	v_mfma_f32_16x16x32_bf16 v[118:121], v[168:171], v[176:179], v[118:121]
	v_mfma_f32_16x16x32_bf16 v[110:113], v[160:163], v[184:187], v[110:113]
	v_mfma_f32_16x16x32_bf16 v[102:105], v[168:171], v[184:187], v[102:105]
	v_mfma_f32_16x16x32_bf16 v[94:97], v[160:163], v[192:195], v[94:97]
	v_mfma_f32_16x16x32_bf16 v[86:89], v[168:171], v[192:195], v[86:89]
	v_mfma_f32_16x16x32_bf16 v[78:81], v[160:163], v[200:203], v[78:81]
	v_mfma_f32_16x16x32_bf16 v[70:73], v[168:171], v[200:203], v[70:73]
	s_barrier
	s_add_u32 s52, s56, 0x80
	s_addc_u32 s53, s57, 0
	ds_read_b128 v[172:175], v138 offset:49152
	ds_read_b128 v[176:179], v138 offset:50176
	ds_read_b128 v[180:183], v138 offset:51200
	ds_read_b128 v[184:187], v138 offset:52224
	ds_read_b128 v[188:191], v138 offset:53248
	ds_read_b128 v[192:195], v138 offset:54272
	ds_read_b128 v[196:199], v138 offset:55296
	ds_read_b128 v[200:203], v138 offset:56320
	s_mov_b32 s12, m0
	s_mov_b32 m0, s76
	s_nop 4
	global_load_lds_dwordx4 v134, s[52:53]
	s_mov_b32 m0, s12
	s_add_u32 s52, s56, 0x20080
	s_addc_u32 s53, s57, 0
	s_mov_b32 s12, m0
	s_mov_b32 m0, s77
	s_nop 4
	global_load_lds_dwordx4 v134, s[52:53]
	s_mov_b32 m0, s12
	s_add_u32 s52, s56, 0x40080
	s_addc_u32 s53, s57, 0
	s_mov_b32 s12, m0
	s_mov_b32 m0, s80
	s_nop 4
	global_load_lds_dwordx4 v134, s[52:53]
	s_mov_b32 m0, s12
	s_add_u32 s52, s56, 0x60080
	s_addc_u32 s53, s57, 0
	s_mov_b32 s12, m0
	s_mov_b32 m0, s81
	s_nop 4
	global_load_lds_dwordx4 v134, s[52:53]
	s_mov_b32 m0, s12
	s_add_u32 s34, s34, 0x20080
	s_mov_b32 s12, m0
	s_mov_b32 m0, s78
	s_nop 4
	global_load_lds_dwordx4 v1, s[54:55]
	s_mov_b32 m0, s12
	s_addc_u32 s35, s35, 0
	s_mov_b32 s12, m0
	s_mov_b32 m0, s79
	s_nop 4
	global_load_lds_dwordx4 v1, s[34:35]
	s_mov_b32 m0, s12
	s_waitcnt vmcnt(8)
	s_waitcnt lgkmcnt(0)
	s_barrier
	v_mfma_f32_16x16x32_bf16 v[58:61], v[140:143], v[172:175], v[58:61]
	v_mfma_f32_16x16x32_bf16 v[50:53], v[148:151], v[172:175], v[50:53]
	v_mfma_f32_16x16x32_bf16 v[42:45], v[140:143], v[180:183], v[42:45]
	v_mfma_f32_16x16x32_bf16 v[34:37], v[148:151], v[180:183], v[34:37]
	v_mfma_f32_16x16x32_bf16 v[26:29], v[140:143], v[188:191], v[26:29]
	v_mfma_f32_16x16x32_bf16 v[18:21], v[148:151], v[188:191], v[18:21]
	v_mfma_f32_16x16x32_bf16 v[10:13], v[140:143], v[196:199], v[10:13]
	v_mfma_f32_16x16x32_bf16 v[2:5], v[148:151], v[196:199], v[2:5]
	v_mfma_f32_16x16x32_bf16 v[58:61], v[144:147], v[176:179], v[58:61]
	v_mfma_f32_16x16x32_bf16 v[50:53], v[152:155], v[176:179], v[50:53]
	v_mfma_f32_16x16x32_bf16 v[42:45], v[144:147], v[184:187], v[42:45]
	v_mfma_f32_16x16x32_bf16 v[34:37], v[152:155], v[184:187], v[34:37]
	v_mfma_f32_16x16x32_bf16 v[26:29], v[144:147], v[192:195], v[26:29]
	v_mfma_f32_16x16x32_bf16 v[18:21], v[152:155], v[192:195], v[18:21]
	v_mfma_f32_16x16x32_bf16 v[10:13], v[144:147], v[200:203], v[10:13]
	v_mfma_f32_16x16x32_bf16 v[2:5], v[152:155], v[200:203], v[2:5]
	v_mfma_f32_16x16x32_bf16 v[62:65], v[156:159], v[172:175], v[62:65]
	v_mfma_f32_16x16x32_bf16 v[54:57], v[164:167], v[172:175], v[54:57]
	v_mfma_f32_16x16x32_bf16 v[46:49], v[156:159], v[180:183], v[46:49]
	v_mfma_f32_16x16x32_bf16 v[38:41], v[164:167], v[180:183], v[38:41]
	v_mfma_f32_16x16x32_bf16 v[30:33], v[156:159], v[188:191], v[30:33]
	v_mfma_f32_16x16x32_bf16 v[22:25], v[164:167], v[188:191], v[22:25]
	v_mfma_f32_16x16x32_bf16 v[14:17], v[156:159], v[196:199], v[14:17]
	v_mfma_f32_16x16x32_bf16 v[6:9], v[164:167], v[196:199], v[6:9]
	v_mfma_f32_16x16x32_bf16 v[62:65], v[160:163], v[176:179], v[62:65]
	v_mfma_f32_16x16x32_bf16 v[54:57], v[168:171], v[176:179], v[54:57]
	v_mfma_f32_16x16x32_bf16 v[46:49], v[160:163], v[184:187], v[46:49]
	v_mfma_f32_16x16x32_bf16 v[38:41], v[168:171], v[184:187], v[38:41]
	v_mfma_f32_16x16x32_bf16 v[30:33], v[160:163], v[192:195], v[30:33]
	v_mfma_f32_16x16x32_bf16 v[22:25], v[168:171], v[192:195], v[22:25]
	v_mfma_f32_16x16x32_bf16 v[14:17], v[160:163], v[200:203], v[14:17]
	v_mfma_f32_16x16x32_bf16 v[6:9], v[168:171], v[200:203], v[6:9]
	s_barrier
	s_add_i32 s89, s89, 2
	s_add_u32 s87, s87, 0x100
	s_addc_u32 s88, s88, 0
	s_cmp_gt_u32 s89, 13
	s_mov_b64 s[52:53], s[0:1]
	s_cbranch_scc0 .LBB0_156
	s_and_b64 vcc, exec, s[8:9]
	s_cbranch_vccz .LBB0_159
	s_barrier

.LBB0_236:
	ds_read_b128 v[138:141], v132
	ds_read_b128 v[142:145], v132 offset:1024
	ds_read_b128 v[146:149], v132 offset:2048
	ds_read_b128 v[150:153], v132 offset:3072
	ds_read_b128 v[154:157], v133
	ds_read_b128 v[158:161], v133 offset:1024
	ds_read_b128 v[166:169], v133 offset:2048
	ds_read_b128 v[170:173], v133 offset:3072
	s_add_u32 s0, s52, 0xea350080
	s_addc_u32 s1, s53, -1
	s_cmp_lg_u32 s92, 40
	s_cselect_b32 s3, s0, 0
	s_cselect_b32 s2, s1, 0
	s_add_u32 s0, s10, s3
	s_addc_u32 s1, s11, s2
	s_add_u32 s34, s0, 0x80
	s_addc_u32 s35, s1, 0
	s_add_u32 s54, s6, s3
	s_addc_u32 s55, s7, s2
	ds_read_b128 v[174:177], v134
	ds_read_b128 v[184:187], v134 offset:1024
	ds_read_b128 v[188:191], v134 offset:2048
	ds_read_b128 v[192:195], v134 offset:3072
	ds_read_b128 v[196:199], v134 offset:4096
	ds_read_b128 v[200:203], v134 offset:5120
	ds_read_b128 v[204:207], v134 offset:6144
	ds_read_b128 v[208:211], v134 offset:7168
	s_add_u32 s94, s90, s52
	s_addc_u32 s95, s91, s53
	s_mov_b32 s2, m0
	s_mov_b32 m0, s89
	s_nop 4
	global_load_lds_dwordx4 v130, s[94:95]
	s_mov_b32 m0, s2
	s_add_u32 s94, s94, 0x58000
	s_addc_u32 s95, s95, 0
	s_add_i32 s2, s65, 0xe000
	s_mov_b32 s3, m0
	s_mov_b32 m0, s2
	s_nop 4
	global_load_lds_dwordx4 v130, s[94:95]
	s_mov_b32 m0, s3
	s_waitcnt vmcnt(8)
	s_waitcnt lgkmcnt(0)
	s_barrier
	v_mfma_f32_16x16x32_bf16 v[2:5], v[138:141], v[174:177], v[2:5]
	v_mfma_f32_16x16x32_bf16 v[6:9], v[146:149], v[174:177], v[6:9]
	v_mfma_f32_16x16x32_bf16 v[30:33], v[138:141], v[188:191], v[30:33]
	v_mfma_f32_16x16x32_bf16 v[34:37], v[146:149], v[188:191], v[34:37]
	v_mfma_f32_16x16x32_bf16 v[54:57], v[138:141], v[196:199], v[54:57]
	v_mfma_f32_16x16x32_bf16 v[50:53], v[146:149], v[196:199], v[50:53]
	v_mfma_f32_16x16x32_bf16 v[70:73], v[138:141], v[204:207], v[70:73]
	v_mfma_f32_16x16x32_bf16 v[62:65], v[146:149], v[204:207], v[62:65]
	v_mfma_f32_16x16x32_bf16 v[2:5], v[142:145], v[184:187], v[2:5]
	v_mfma_f32_16x16x32_bf16 v[6:9], v[150:153], v[184:187], v[6:9]
	v_mfma_f32_16x16x32_bf16 v[30:33], v[142:145], v[192:195], v[30:33]
	v_mfma_f32_16x16x32_bf16 v[34:37], v[150:153], v[192:195], v[34:37]
	v_mfma_f32_16x16x32_bf16 v[54:57], v[142:145], v[200:203], v[54:57]
	v_mfma_f32_16x16x32_bf16 v[50:53], v[150:153], v[200:203], v[50:53]
	v_mfma_f32_16x16x32_bf16 v[70:73], v[142:145], v[208:211], v[70:73]
	v_mfma_f32_16x16x32_bf16 v[62:65], v[150:153], v[208:211], v[62:65]
	v_mfma_f32_16x16x32_bf16 v[10:13], v[154:157], v[174:177], v[10:13]
	v_mfma_f32_16x16x32_bf16 v[14:17], v[166:169], v[174:177], v[14:17]
	v_mfma_f32_16x16x32_bf16 v[22:25], v[154:157], v[188:191], v[22:25]
	v_mfma_f32_16x16x32_bf16 v[18:21], v[166:169], v[188:191], v[18:21]
	v_mfma_f32_16x16x32_bf16 v[38:41], v[154:157], v[196:199], v[38:41]
	v_mfma_f32_16x16x32_bf16 v[26:29], v[166:169], v[196:199], v[26:29]
	v_mfma_f32_16x16x32_bf16 v[46:49], v[154:157], v[204:207], v[46:49]
	v_mfma_f32_16x16x32_bf16 v[42:45], v[166:169], v[204:207], v[42:45]
	v_mfma_f32_16x16x32_bf16 v[10:13], v[158:161], v[184:187], v[10:13]
	v_mfma_f32_16x16x32_bf16 v[14:17], v[170:173], v[184:187], v[14:17]
	v_mfma_f32_16x16x32_bf16 v[22:25], v[158:161], v[192:195], v[22:25]
	v_mfma_f32_16x16x32_bf16 v[18:21], v[170:173], v[192:195], v[18:21]
	v_mfma_f32_16x16x32_bf16 v[38:41], v[158:161], v[200:203], v[38:41]
	v_mfma_f32_16x16x32_bf16 v[26:29], v[170:173], v[200:203], v[26:29]
	v_mfma_f32_16x16x32_bf16 v[46:49], v[158:161], v[208:211], v[46:49]
	v_mfma_f32_16x16x32_bf16 v[42:45], v[170:173], v[208:211], v[42:45]
	s_barrier
	s_add_u32 s94, s54, 0x58000
	ds_read_b128 v[174:177], v134 offset:16384
	ds_read_b128 v[184:187], v134 offset:17408
	ds_read_b128 v[188:191], v134 offset:18432
	ds_read_b128 v[192:195], v134 offset:19456
	ds_read_b128 v[196:199], v134 offset:20480
	ds_read_b128 v[200:203], v134 offset:21504
	ds_read_b128 v[204:207], v134 offset:22528
	ds_read_b128 v[208:211], v134 offset:23552
	s_mov_b32 s2, m0
	s_mov_b32 m0, s73
	s_nop 4
	global_load_lds_dwordx4 v131, s[54:55]
	s_mov_b32 m0, s2
	s_addc_u32 s95, s55, 0
	s_mov_b32 s2, m0
	s_mov_b32 m0, s74
	s_nop 4
	global_load_lds_dwordx4 v131, s[94:95]
	s_mov_b32 m0, s2
	s_add_u32 s94, s54, 0xb0000
	s_addc_u32 s95, s55, 0
	s_mov_b32 s2, m0
	s_mov_b32 m0, s75
	s_nop 4
	global_load_lds_dwordx4 v131, s[94:95]
	s_mov_b32 m0, s2
	s_add_u32 s94, s54, 0x108000
	s_addc_u32 s95, s55, 0
	s_mov_b32 s2, m0
	s_mov_b32 m0, s76
	s_nop 4
	global_load_lds_dwordx4 v131, s[94:95]
	s_mov_b32 m0, s2
	s_add_u32 s94, s0, 0x58000
	s_mov_b32 s2, m0
	s_mov_b32 m0, s65
	s_nop 4
	global_load_lds_dwordx4 v130, s[0:1]
	s_mov_b32 m0, s2
	s_addc_u32 s95, s1, 0
	s_mov_b32 s2, m0
	s_mov_b32 m0, s77
	s_nop 4
	global_load_lds_dwordx4 v130, s[94:95]
	s_mov_b32 m0, s2
	s_waitcnt vmcnt(8)
	s_waitcnt lgkmcnt(0)
	s_barrier
	v_mfma_f32_16x16x32_bf16 v[82:85], v[138:141], v[174:177], v[82:85]
	v_mfma_f32_16x16x32_bf16 v[74:77], v[146:149], v[174:177], v[74:77]
	v_mfma_f32_16x16x32_bf16 v[98:101], v[138:141], v[188:191], v[98:101]
	v_mfma_f32_16x16x32_bf16 v[90:93], v[146:149], v[188:191], v[90:93]
	v_mfma_f32_16x16x32_bf16 v[114:117], v[138:141], v[196:199], v[114:117]
	v_mfma_f32_16x16x32_bf16 v[110:113], v[146:149], v[196:199], v[110:113]
	v_mfma_f32_16x16x32_bf16 v[126:129], v[138:141], v[204:207], v[126:129]
	v_mfma_f32_16x16x32_bf16 v[122:125], v[146:149], v[204:207], v[122:125]
	v_mfma_f32_16x16x32_bf16 v[82:85], v[142:145], v[184:187], v[82:85]
	v_mfma_f32_16x16x32_bf16 v[74:77], v[150:153], v[184:187], v[74:77]
	v_mfma_f32_16x16x32_bf16 v[98:101], v[142:145], v[192:195], v[98:101]
	v_mfma_f32_16x16x32_bf16 v[90:93], v[150:153], v[192:195], v[90:93]
	v_mfma_f32_16x16x32_bf16 v[114:117], v[142:145], v[200:203], v[114:117]
	v_mfma_f32_16x16x32_bf16 v[110:113], v[150:153], v[200:203], v[110:113]
	v_mfma_f32_16x16x32_bf16 v[126:129], v[142:145], v[208:211], v[126:129]
	v_mfma_f32_16x16x32_bf16 v[122:125], v[150:153], v[208:211], v[122:125]
	v_mfma_f32_16x16x32_bf16 v[66:69], v[154:157], v[174:177], v[66:69]
	v_mfma_f32_16x16x32_bf16 v[58:61], v[166:169], v[174:177], v[58:61]
	v_mfma_f32_16x16x32_bf16 v[86:89], v[154:157], v[188:191], v[86:89]
	v_mfma_f32_16x16x32_bf16 v[78:81], v[166:169], v[188:191], v[78:81]
	v_mfma_f32_16x16x32_bf16 v[102:105], v[154:157], v[196:199], v[102:105]
	v_mfma_f32_16x16x32_bf16 v[94:97], v[166:169], v[196:199], v[94:97]
	v_mfma_f32_16x16x32_bf16 v[118:121], v[154:157], v[204:207], v[118:121]
	v_mfma_f32_16x16x32_bf16 v[106:109], v[166:169], v[204:207], v[106:109]
	v_mfma_f32_16x16x32_bf16 v[66:69], v[158:161], v[184:187], v[66:69]
	v_mfma_f32_16x16x32_bf16 v[58:61], v[170:173], v[184:187], v[58:61]
	v_mfma_f32_16x16x32_bf16 v[86:89], v[158:161], v[192:195], v[86:89]
	v_mfma_f32_16x16x32_bf16 v[78:81], v[170:173], v[192:195], v[78:81]
	v_mfma_f32_16x16x32_bf16 v[102:105], v[158:161], v[200:203], v[102:105]
	v_mfma_f32_16x16x32_bf16 v[94:97], v[170:173], v[200:203], v[94:97]
	v_mfma_f32_16x16x32_bf16 v[118:121], v[158:161], v[208:211], v[118:121]
	v_mfma_f32_16x16x32_bf16 v[106:109], v[170:173], v[208:211], v[106:109]
	s_barrier
	ds_read_b128 v[138:141], v135
	ds_read_b128 v[142:145], v135 offset:1024
	ds_read_b128 v[146:149], v135 offset:2048
	ds_read_b128 v[150:153], v135 offset:3072
	ds_read_b128 v[154:157], v136
	ds_read_b128 v[158:161], v136 offset:1024
	ds_read_b128 v[166:169], v136 offset:2048
	ds_read_b128 v[170:173], v136 offset:3072
	ds_read_b128 v[174:177], v134 offset:32768
	ds_read_b128 v[184:187], v134 offset:33792
	ds_read_b128 v[188:191], v134 offset:34816
	ds_read_b128 v[192:195], v134 offset:35840
	ds_read_b128 v[196:199], v134 offset:36864
	ds_read_b128 v[200:203], v134 offset:37888
	ds_read_b128 v[204:207], v134 offset:38912
	ds_read_b128 v[208:211], v134 offset:39936
	s_add_u32 s94, s0, 0xb0000
	s_addc_u32 s95, s1, 0
	s_mov_b32 s2, m0
	s_mov_b32 m0, s78
	s_nop 4
	global_load_lds_dwordx4 v130, s[94:95]
	s_mov_b32 m0, s2
	s_add_u32 s94, s0, 0x108000
	s_addc_u32 s95, s1, 0
	s_mov_b32 s2, m0
	s_mov_b32 m0, s80
	s_nop 4
	global_load_lds_dwordx4 v130, s[94:95]
	s_mov_b32 m0, s2
	s_waitcnt vmcnt(8)
	s_waitcnt lgkmcnt(0)
	s_barrier
	v_mfma_f32_16x16x32_bf16 v[2:5], v[138:141], v[174:177], v[2:5]
	v_mfma_f32_16x16x32_bf16 v[6:9], v[146:149], v[174:177], v[6:9]
	v_mfma_f32_16x16x32_bf16 v[30:33], v[138:141], v[188:191], v[30:33]
	v_mfma_f32_16x16x32_bf16 v[34:37], v[146:149], v[188:191], v[34:37]
	v_mfma_f32_16x16x32_bf16 v[54:57], v[138:141], v[196:199], v[54:57]
	v_mfma_f32_16x16x32_bf16 v[50:53], v[146:149], v[196:199], v[50:53]
	v_mfma_f32_16x16x32_bf16 v[70:73], v[138:141], v[204:207], v[70:73]
	v_mfma_f32_16x16x32_bf16 v[62:65], v[146:149], v[204:207], v[62:65]
	v_mfma_f32_16x16x32_bf16 v[2:5], v[142:145], v[184:187], v[2:5]
	v_mfma_f32_16x16x32_bf16 v[6:9], v[150:153], v[184:187], v[6:9]
	v_mfma_f32_16x16x32_bf16 v[30:33], v[142:145], v[192:195], v[30:33]
	v_mfma_f32_16x16x32_bf16 v[34:37], v[150:153], v[192:195], v[34:37]
	v_mfma_f32_16x16x32_bf16 v[54:57], v[142:145], v[200:203], v[54:57]
	v_mfma_f32_16x16x32_bf16 v[50:53], v[150:153], v[200:203], v[50:53]
	v_mfma_f32_16x16x32_bf16 v[70:73], v[142:145], v[208:211], v[70:73]
	v_mfma_f32_16x16x32_bf16 v[62:65], v[150:153], v[208:211], v[62:65]
	v_mfma_f32_16x16x32_bf16 v[10:13], v[154:157], v[174:177], v[10:13]
	v_mfma_f32_16x16x32_bf16 v[14:17], v[166:169], v[174:177], v[14:17]
	v_mfma_f32_16x16x32_bf16 v[22:25], v[154:157], v[188:191], v[22:25]
	v_mfma_f32_16x16x32_bf16 v[18:21], v[166:169], v[188:191], v[18:21]
	v_mfma_f32_16x16x32_bf16 v[38:41], v[154:157], v[196:199], v[38:41]
	v_mfma_f32_16x16x32_bf16 v[26:29], v[166:169], v[196:199], v[26:29]
	v_mfma_f32_16x16x32_bf16 v[46:49], v[154:157], v[204:207], v[46:49]
	v_mfma_f32_16x16x32_bf16 v[42:45], v[166:169], v[204:207], v[42:45]
	v_mfma_f32_16x16x32_bf16 v[10:13], v[158:161], v[184:187], v[10:13]
	v_mfma_f32_16x16x32_bf16 v[14:17], v[170:173], v[184:187], v[14:17]
	v_mfma_f32_16x16x32_bf16 v[22:25], v[158:161], v[192:195], v[22:25]
	v_mfma_f32_16x16x32_bf16 v[18:21], v[170:173], v[192:195], v[18:21]
	v_mfma_f32_16x16x32_bf16 v[38:41], v[158:161], v[200:203], v[38:41]
	v_mfma_f32_16x16x32_bf16 v[26:29], v[170:173], v[200:203], v[26:29]
	v_mfma_f32_16x16x32_bf16 v[46:49], v[158:161], v[208:211], v[46:49]
	v_mfma_f32_16x16x32_bf16 v[42:45], v[170:173], v[208:211], v[42:45]
	s_barrier
	s_add_u32 s94, s54, 0x80
	s_addc_u32 s95, s55, 0
	ds_read_b128 v[174:177], v134 offset:49152
	ds_read_b128 v[184:187], v134 offset:50176
	ds_read_b128 v[188:191], v134 offset:51200
	ds_read_b128 v[192:195], v134 offset:52224
	ds_read_b128 v[196:199], v134 offset:53248
	ds_read_b128 v[200:203], v134 offset:54272
	ds_read_b128 v[204:207], v134 offset:55296
	ds_read_b128 v[208:211], v134 offset:56320
	s_mov_b32 s2, m0
	s_mov_b32 m0, s81
	s_nop 4
	global_load_lds_dwordx4 v131, s[94:95]
	s_mov_b32 m0, s2
	s_add_u32 s94, s54, 0x58080
	s_addc_u32 s95, s55, 0
	s_mov_b32 s2, m0
	s_mov_b32 m0, s84
	s_nop 4
	global_load_lds_dwordx4 v131, s[94:95]
	s_mov_b32 m0, s2
	s_add_u32 s94, s54, 0xb0080
	s_addc_u32 s95, s55, 0
	s_mov_b32 s2, m0
	s_mov_b32 m0, s87
	s_nop 4
	global_load_lds_dwordx4 v131, s[94:95]
	s_mov_b32 m0, s2
	s_add_u32 s54, s54, 0x108080
	s_addc_u32 s55, s55, 0
	s_mov_b32 s2, m0
	s_mov_b32 m0, s88
	s_nop 4
	global_load_lds_dwordx4 v131, s[54:55]
	s_mov_b32 m0, s2
	s_add_u32 s0, s0, 0x58080
	s_mov_b32 s2, m0
	s_mov_b32 m0, s85
	s_nop 4
	global_load_lds_dwordx4 v130, s[34:35]
	s_mov_b32 m0, s2
	s_addc_u32 s1, s1, 0
	s_mov_b32 s2, m0
	s_mov_b32 m0, s86
	s_nop 4
	global_load_lds_dwordx4 v130, s[0:1]
	s_mov_b32 m0, s2
	s_waitcnt vmcnt(8)
	s_waitcnt lgkmcnt(0)
	s_barrier
	v_mfma_f32_16x16x32_bf16 v[82:85], v[138:141], v[174:177], v[82:85]
	v_mfma_f32_16x16x32_bf16 v[74:77], v[146:149], v[174:177], v[74:77]
	v_mfma_f32_16x16x32_bf16 v[98:101], v[138:141], v[188:191], v[98:101]
	v_mfma_f32_16x16x32_bf16 v[90:93], v[146:149], v[188:191], v[90:93]
	v_mfma_f32_16x16x32_bf16 v[114:117], v[138:141], v[196:199], v[114:117]
	v_mfma_f32_16x16x32_bf16 v[110:113], v[146:149], v[196:199], v[110:113]
	v_mfma_f32_16x16x32_bf16 v[126:129], v[138:141], v[204:207], v[126:129]
	v_mfma_f32_16x16x32_bf16 v[122:125], v[146:149], v[204:207], v[122:125]
	v_mfma_f32_16x16x32_bf16 v[82:85], v[142:145], v[184:187], v[82:85]
	v_mfma_f32_16x16x32_bf16 v[74:77], v[150:153], v[184:187], v[74:77]
	v_mfma_f32_16x16x32_bf16 v[98:101], v[142:145], v[192:195], v[98:101]
	v_mfma_f32_16x16x32_bf16 v[90:93], v[150:153], v[192:195], v[90:93]
	v_mfma_f32_16x16x32_bf16 v[114:117], v[142:145], v[200:203], v[114:117]
	v_mfma_f32_16x16x32_bf16 v[110:113], v[150:153], v[200:203], v[110:113]
	v_mfma_f32_16x16x32_bf16 v[126:129], v[142:145], v[208:211], v[126:129]
	v_mfma_f32_16x16x32_bf16 v[122:125], v[150:153], v[208:211], v[122:125]
	v_mfma_f32_16x16x32_bf16 v[66:69], v[154:157], v[174:177], v[66:69]
	v_mfma_f32_16x16x32_bf16 v[58:61], v[166:169], v[174:177], v[58:61]
	v_mfma_f32_16x16x32_bf16 v[86:89], v[154:157], v[188:191], v[86:89]
	v_mfma_f32_16x16x32_bf16 v[78:81], v[166:169], v[188:191], v[78:81]
	v_mfma_f32_16x16x32_bf16 v[102:105], v[154:157], v[196:199], v[102:105]
	v_mfma_f32_16x16x32_bf16 v[94:97], v[166:169], v[196:199], v[94:97]
	v_mfma_f32_16x16x32_bf16 v[118:121], v[154:157], v[204:207], v[118:121]
	v_mfma_f32_16x16x32_bf16 v[106:109], v[166:169], v[204:207], v[106:109]
	v_mfma_f32_16x16x32_bf16 v[66:69], v[158:161], v[184:187], v[66:69]
	v_mfma_f32_16x16x32_bf16 v[58:61], v[170:173], v[184:187], v[58:61]
	v_mfma_f32_16x16x32_bf16 v[86:89], v[158:161], v[192:195], v[86:89]
	v_mfma_f32_16x16x32_bf16 v[78:81], v[170:173], v[192:195], v[78:81]
	v_mfma_f32_16x16x32_bf16 v[102:105], v[158:161], v[200:203], v[102:105]
	v_mfma_f32_16x16x32_bf16 v[94:97], v[170:173], v[200:203], v[94:97]
	v_mfma_f32_16x16x32_bf16 v[118:121], v[158:161], v[208:211], v[118:121]
	v_mfma_f32_16x16x32_bf16 v[106:109], v[170:173], v[208:211], v[106:109]
	s_barrier
	s_add_i32 s92, s92, 2
	s_add_u32 s52, s52, 0x100
	s_addc_u32 s53, s53, 0
	s_cmp_lt_u32 s92, 42
	s_cbranch_scc1 .LBB0_236
	s_waitcnt vmcnt(0)
	s_cmpk_gt_u32 s63, 0xff
	s_cbranch_scc1 .LBB0_239
	s_barrier

.LBB0_419:
	v_add_u32_e32 v134, 0x10000, v145
	ds_read_b128 v[136:139], v134
	ds_read_b128 v[148:151], v134 offset:1024
	ds_read_b128 v[152:155], v134 offset:2048
	ds_read_b128 v[156:159], v134 offset:3072
	v_add_u32_e32 v134, 0x14000, v145
	ds_read_b128 v[160:163], v134
	ds_read_b128 v[164:167], v134 offset:1024
	ds_read_b128 v[168:171], v134 offset:2048
	ds_read_b128 v[172:175], v134 offset:3072
	s_add_u32 s0, s50, 0x100
	s_addc_u32 s1, s51, 0
	s_cmp_eq_u32 s81, 12
	s_cselect_b32 s34, s15, s0
	s_cselect_b32 s35, s14, s1
	s_cselect_b32 s54, s37, s79
	s_cselect_b32 s55, s27, s80
	s_add_u32 s52, s34, 0x80
	s_addc_u32 s53, s35, 0
	ds_read_b128 v[176:179], v146
	ds_read_b128 v[180:183], v146 offset:1024
	ds_read_b128 v[184:187], v146 offset:2048
	ds_read_b128 v[188:191], v146 offset:3072
	ds_read_b128 v[192:195], v146 offset:4096
	ds_read_b128 v[196:199], v146 offset:5120
	ds_read_b128 v[200:203], v146 offset:6144
	ds_read_b128 v[204:207], v146 offset:7168
	s_add_u32 s84, s50, 0x40080
	s_addc_u32 s85, s51, 0
	s_mov_b32 s2, m0
	s_mov_b32 m0, s76
	s_nop 4
	global_load_lds_dwordx4 v1, s[84:85]
	s_mov_b32 m0, s2
	s_add_u32 s50, s50, 0x60080
	s_addc_u32 s51, s51, 0
	s_add_i32 s2, s45, 0xe000
	s_mov_b32 s3, m0
	s_mov_b32 m0, s2
	s_nop 4
	global_load_lds_dwordx4 v1, s[50:51]
	s_mov_b32 m0, s3
	s_waitcnt vmcnt(8)
	s_waitcnt lgkmcnt(0)
	s_barrier
	v_mfma_f32_16x16x32_bf16 v[122:125], v[136:139], v[176:179], v[122:125]
	v_mfma_f32_16x16x32_bf16 v[114:117], v[152:155], v[176:179], v[114:117]
	v_mfma_f32_16x16x32_bf16 v[106:109], v[136:139], v[184:187], v[106:109]
	v_mfma_f32_16x16x32_bf16 v[98:101], v[152:155], v[184:187], v[98:101]
	v_mfma_f32_16x16x32_bf16 v[90:93], v[136:139], v[192:195], v[90:93]
	v_mfma_f32_16x16x32_bf16 v[82:85], v[152:155], v[192:195], v[82:85]
	v_mfma_f32_16x16x32_bf16 v[74:77], v[136:139], v[200:203], v[74:77]
	v_mfma_f32_16x16x32_bf16 v[66:69], v[152:155], v[200:203], v[66:69]
	v_mfma_f32_16x16x32_bf16 v[122:125], v[148:151], v[180:183], v[122:125]
	v_mfma_f32_16x16x32_bf16 v[114:117], v[156:159], v[180:183], v[114:117]
	v_mfma_f32_16x16x32_bf16 v[106:109], v[148:151], v[188:191], v[106:109]
	v_mfma_f32_16x16x32_bf16 v[98:101], v[156:159], v[188:191], v[98:101]
	v_mfma_f32_16x16x32_bf16 v[90:93], v[148:151], v[196:199], v[90:93]
	v_mfma_f32_16x16x32_bf16 v[82:85], v[156:159], v[196:199], v[82:85]
	v_mfma_f32_16x16x32_bf16 v[74:77], v[148:151], v[204:207], v[74:77]
	v_mfma_f32_16x16x32_bf16 v[66:69], v[156:159], v[204:207], v[66:69]
	v_mfma_f32_16x16x32_bf16 v[126:129], v[160:163], v[176:179], v[126:129]
	v_mfma_f32_16x16x32_bf16 v[118:121], v[168:171], v[176:179], v[118:121]
	v_mfma_f32_16x16x32_bf16 v[110:113], v[160:163], v[184:187], v[110:113]
	v_mfma_f32_16x16x32_bf16 v[102:105], v[168:171], v[184:187], v[102:105]
	v_mfma_f32_16x16x32_bf16 v[94:97], v[160:163], v[192:195], v[94:97]
	v_mfma_f32_16x16x32_bf16 v[86:89], v[168:171], v[192:195], v[86:89]
	v_mfma_f32_16x16x32_bf16 v[78:81], v[160:163], v[200:203], v[78:81]
	v_mfma_f32_16x16x32_bf16 v[70:73], v[168:171], v[200:203], v[70:73]
	v_mfma_f32_16x16x32_bf16 v[126:129], v[164:167], v[180:183], v[126:129]
	v_mfma_f32_16x16x32_bf16 v[118:121], v[172:175], v[180:183], v[118:121]
	v_mfma_f32_16x16x32_bf16 v[110:113], v[164:167], v[188:191], v[110:113]
	v_mfma_f32_16x16x32_bf16 v[102:105], v[172:175], v[188:191], v[102:105]
	v_mfma_f32_16x16x32_bf16 v[94:97], v[164:167], v[196:199], v[94:97]
	v_mfma_f32_16x16x32_bf16 v[86:89], v[172:175], v[196:199], v[86:89]
	v_mfma_f32_16x16x32_bf16 v[78:81], v[164:167], v[204:207], v[78:81]
	v_mfma_f32_16x16x32_bf16 v[70:73], v[172:175], v[204:207], v[70:73]
	s_barrier
	s_add_u32 s50, s54, 0x20000
	ds_read_b128 v[176:179], v146 offset:16384
	ds_read_b128 v[180:183], v146 offset:17408
	ds_read_b128 v[184:187], v146 offset:18432
	ds_read_b128 v[188:191], v146 offset:19456
	ds_read_b128 v[192:195], v146 offset:20480
	ds_read_b128 v[196:199], v146 offset:21504
	ds_read_b128 v[200:203], v146 offset:22528
	ds_read_b128 v[204:207], v146 offset:23552
	s_mov_b32 s2, m0
	s_mov_b32 m0, s58
	s_nop 4
	global_load_lds_dwordx4 v142, s[54:55]
	s_mov_b32 m0, s2
	s_addc_u32 s51, s55, 0
	s_mov_b32 s2, m0
	s_mov_b32 m0, s59
	s_nop 4
	global_load_lds_dwordx4 v142, s[50:51]
	s_mov_b32 m0, s2
	s_add_u32 s50, s54, 0x40000
	s_addc_u32 s51, s55, 0
	s_mov_b32 s2, m0
	s_mov_b32 m0, s60
	s_nop 4
	global_load_lds_dwordx4 v142, s[50:51]
	s_mov_b32 m0, s2
	s_add_u32 s50, s54, 0x60000
	s_addc_u32 s51, s55, 0
	s_mov_b32 s2, m0
	s_mov_b32 m0, s61
	s_nop 4
	global_load_lds_dwordx4 v142, s[50:51]
	s_mov_b32 m0, s2
	s_add_u32 s50, s34, 0x20000
	s_mov_b32 s2, m0
	s_mov_b32 m0, s45
	s_nop 4
	global_load_lds_dwordx4 v1, s[34:35]
	s_mov_b32 m0, s2
	s_addc_u32 s51, s35, 0
	s_mov_b32 s2, m0
	s_mov_b32 m0, s62
	s_nop 4
	global_load_lds_dwordx4 v1, s[50:51]
	s_mov_b32 m0, s2
	s_waitcnt vmcnt(8)
	s_waitcnt lgkmcnt(0)
	s_barrier
	v_mfma_f32_16x16x32_bf16 v[58:61], v[136:139], v[176:179], v[58:61]
	v_mfma_f32_16x16x32_bf16 v[50:53], v[152:155], v[176:179], v[50:53]
	v_mfma_f32_16x16x32_bf16 v[42:45], v[136:139], v[184:187], v[42:45]
	v_mfma_f32_16x16x32_bf16 v[34:37], v[152:155], v[184:187], v[34:37]
	v_mfma_f32_16x16x32_bf16 v[26:29], v[136:139], v[192:195], v[26:29]
	v_mfma_f32_16x16x32_bf16 v[18:21], v[152:155], v[192:195], v[18:21]
	v_mfma_f32_16x16x32_bf16 v[10:13], v[136:139], v[200:203], v[10:13]
	v_mfma_f32_16x16x32_bf16 v[2:5], v[152:155], v[200:203], v[2:5]
	v_mfma_f32_16x16x32_bf16 v[58:61], v[148:151], v[180:183], v[58:61]
	v_mfma_f32_16x16x32_bf16 v[50:53], v[156:159], v[180:183], v[50:53]
	v_mfma_f32_16x16x32_bf16 v[42:45], v[148:151], v[188:191], v[42:45]
	v_mfma_f32_16x16x32_bf16 v[34:37], v[156:159], v[188:191], v[34:37]
	v_mfma_f32_16x16x32_bf16 v[26:29], v[148:151], v[196:199], v[26:29]
	v_mfma_f32_16x16x32_bf16 v[18:21], v[156:159], v[196:199], v[18:21]
	v_mfma_f32_16x16x32_bf16 v[10:13], v[148:151], v[204:207], v[10:13]
	v_mfma_f32_16x16x32_bf16 v[2:5], v[156:159], v[204:207], v[2:5]
	v_mfma_f32_16x16x32_bf16 v[62:65], v[160:163], v[176:179], v[62:65]
	v_mfma_f32_16x16x32_bf16 v[54:57], v[168:171], v[176:179], v[54:57]
	v_mfma_f32_16x16x32_bf16 v[46:49], v[160:163], v[184:187], v[46:49]
	v_mfma_f32_16x16x32_bf16 v[38:41], v[168:171], v[184:187], v[38:41]
	v_mfma_f32_16x16x32_bf16 v[30:33], v[160:163], v[192:195], v[30:33]
	v_mfma_f32_16x16x32_bf16 v[22:25], v[168:171], v[192:195], v[22:25]
	v_mfma_f32_16x16x32_bf16 v[14:17], v[160:163], v[200:203], v[14:17]
	v_mfma_f32_16x16x32_bf16 v[6:9], v[168:171], v[200:203], v[6:9]
	v_mfma_f32_16x16x32_bf16 v[62:65], v[164:167], v[180:183], v[62:65]
	v_mfma_f32_16x16x32_bf16 v[54:57], v[172:175], v[180:183], v[54:57]
	v_mfma_f32_16x16x32_bf16 v[46:49], v[164:167], v[188:191], v[46:49]
	v_mfma_f32_16x16x32_bf16 v[38:41], v[172:175], v[188:191], v[38:41]
	v_mfma_f32_16x16x32_bf16 v[30:33], v[164:167], v[196:199], v[30:33]
	v_mfma_f32_16x16x32_bf16 v[22:25], v[172:175], v[196:199], v[22:25]
	v_mfma_f32_16x16x32_bf16 v[14:17], v[164:167], v[204:207], v[14:17]
	v_mfma_f32_16x16x32_bf16 v[6:9], v[172:175], v[204:207], v[6:9]
	s_barrier
	v_add_u32_e32 v134, 0x18000, v145
	ds_read_b128 v[136:139], v134
	ds_read_b128 v[148:151], v134 offset:1024
	ds_read_b128 v[152:155], v134 offset:2048
	ds_read_b128 v[156:159], v134 offset:3072
	v_add_u32_e32 v134, 0x1c000, v145
	ds_read_b128 v[160:163], v134
	ds_read_b128 v[164:167], v134 offset:1024
	ds_read_b128 v[168:171], v134 offset:2048
	ds_read_b128 v[172:175], v134 offset:3072
	ds_read_b128 v[176:179], v146 offset:32768
	ds_read_b128 v[180:183], v146 offset:33792
	ds_read_b128 v[184:187], v146 offset:34816
	ds_read_b128 v[188:191], v146 offset:35840
	ds_read_b128 v[192:195], v146 offset:36864
	ds_read_b128 v[196:199], v146 offset:37888
	ds_read_b128 v[200:203], v146 offset:38912
	ds_read_b128 v[204:207], v146 offset:39936
	s_add_u32 s50, s34, 0x40000
	s_addc_u32 s51, s35, 0
	s_mov_b32 s2, m0
	s_mov_b32 m0, s63
	s_nop 4
	global_load_lds_dwordx4 v1, s[50:51]
	s_mov_b32 m0, s2
	s_add_u32 s50, s34, 0x60000
	s_addc_u32 s51, s35, 0
	s_mov_b32 s2, m0
	s_mov_b32 m0, s64
	s_nop 4
	global_load_lds_dwordx4 v1, s[50:51]
	s_mov_b32 m0, s2
	s_waitcnt vmcnt(8)
	s_waitcnt lgkmcnt(0)
	s_barrier
	v_mfma_f32_16x16x32_bf16 v[122:125], v[136:139], v[176:179], v[122:125]
	v_mfma_f32_16x16x32_bf16 v[114:117], v[152:155], v[176:179], v[114:117]
	v_mfma_f32_16x16x32_bf16 v[106:109], v[136:139], v[184:187], v[106:109]
	v_mfma_f32_16x16x32_bf16 v[98:101], v[152:155], v[184:187], v[98:101]
	v_mfma_f32_16x16x32_bf16 v[90:93], v[136:139], v[192:195], v[90:93]
	v_mfma_f32_16x16x32_bf16 v[82:85], v[152:155], v[192:195], v[82:85]
	v_mfma_f32_16x16x32_bf16 v[74:77], v[136:139], v[200:203], v[74:77]
	v_mfma_f32_16x16x32_bf16 v[66:69], v[152:155], v[200:203], v[66:69]
	v_mfma_f32_16x16x32_bf16 v[122:125], v[148:151], v[180:183], v[122:125]
	v_mfma_f32_16x16x32_bf16 v[114:117], v[156:159], v[180:183], v[114:117]
	v_mfma_f32_16x16x32_bf16 v[106:109], v[148:151], v[188:191], v[106:109]
	v_mfma_f32_16x16x32_bf16 v[98:101], v[156:159], v[188:191], v[98:101]
	v_mfma_f32_16x16x32_bf16 v[90:93], v[148:151], v[196:199], v[90:93]
	v_mfma_f32_16x16x32_bf16 v[82:85], v[156:159], v[196:199], v[82:85]
	v_mfma_f32_16x16x32_bf16 v[74:77], v[148:151], v[204:207], v[74:77]
	v_mfma_f32_16x16x32_bf16 v[66:69], v[156:159], v[204:207], v[66:69]
	v_mfma_f32_16x16x32_bf16 v[126:129], v[160:163], v[176:179], v[126:129]
	v_mfma_f32_16x16x32_bf16 v[118:121], v[168:171], v[176:179], v[118:121]
	v_mfma_f32_16x16x32_bf16 v[110:113], v[160:163], v[184:187], v[110:113]
	v_mfma_f32_16x16x32_bf16 v[102:105], v[168:171], v[184:187], v[102:105]
	v_mfma_f32_16x16x32_bf16 v[94:97], v[160:163], v[192:195], v[94:97]
	v_mfma_f32_16x16x32_bf16 v[86:89], v[168:171], v[192:195], v[86:89]
	v_mfma_f32_16x16x32_bf16 v[78:81], v[160:163], v[200:203], v[78:81]
	v_mfma_f32_16x16x32_bf16 v[70:73], v[168:171], v[200:203], v[70:73]
	v_mfma_f32_16x16x32_bf16 v[126:129], v[164:167], v[180:183], v[126:129]
	v_mfma_f32_16x16x32_bf16 v[118:121], v[172:175], v[180:183], v[118:121]
	v_mfma_f32_16x16x32_bf16 v[110:113], v[164:167], v[188:191], v[110:113]
	v_mfma_f32_16x16x32_bf16 v[102:105], v[172:175], v[188:191], v[102:105]
	v_mfma_f32_16x16x32_bf16 v[94:97], v[164:167], v[196:199], v[94:97]
	v_mfma_f32_16x16x32_bf16 v[86:89], v[172:175], v[196:199], v[86:89]
	v_mfma_f32_16x16x32_bf16 v[78:81], v[164:167], v[204:207], v[78:81]
	v_mfma_f32_16x16x32_bf16 v[70:73], v[172:175], v[204:207], v[70:73]
	s_barrier
	s_add_u32 s50, s54, 0x80
	s_addc_u32 s51, s55, 0
	ds_read_b128 v[176:179], v146 offset:49152
	ds_read_b128 v[180:183], v146 offset:50176
	ds_read_b128 v[184:187], v146 offset:51200
	ds_read_b128 v[188:191], v146 offset:52224
	ds_read_b128 v[192:195], v146 offset:53248
	ds_read_b128 v[196:199], v146 offset:54272
	ds_read_b128 v[200:203], v146 offset:55296
	ds_read_b128 v[204:207], v146 offset:56320
	s_mov_b32 s2, m0
	s_mov_b32 m0, s65
	s_nop 4
	global_load_lds_dwordx4 v142, s[50:51]
	s_mov_b32 m0, s2
	s_add_u32 s50, s54, 0x20080
	s_addc_u32 s51, s55, 0
	s_mov_b32 s2, m0
	s_mov_b32 m0, s66
	s_nop 4
	global_load_lds_dwordx4 v142, s[50:51]
	s_mov_b32 m0, s2
	s_add_u32 s50, s54, 0x40080
	s_addc_u32 s51, s55, 0
	s_mov_b32 s2, m0
	s_mov_b32 m0, s74
	s_nop 4
	global_load_lds_dwordx4 v142, s[50:51]
	s_mov_b32 m0, s2
	s_add_u32 s50, s54, 0x60080
	s_addc_u32 s51, s55, 0
	s_mov_b32 s2, m0
	s_mov_b32 m0, s75
	s_nop 4
	global_load_lds_dwordx4 v142, s[50:51]
	s_mov_b32 m0, s2
	s_add_u32 s34, s34, 0x20080
	s_mov_b32 s2, m0
	s_mov_b32 m0, s67
	s_nop 4
	global_load_lds_dwordx4 v1, s[52:53]
	s_mov_b32 m0, s2
	s_addc_u32 s35, s35, 0
	s_mov_b32 s2, m0
	s_mov_b32 m0, s73
	s_nop 4
	global_load_lds_dwordx4 v1, s[34:35]
	s_mov_b32 m0, s2
	s_waitcnt vmcnt(8)
	s_waitcnt lgkmcnt(0)
	s_barrier
	v_mfma_f32_16x16x32_bf16 v[58:61], v[136:139], v[176:179], v[58:61]
	v_mfma_f32_16x16x32_bf16 v[50:53], v[152:155], v[176:179], v[50:53]
	v_mfma_f32_16x16x32_bf16 v[42:45], v[136:139], v[184:187], v[42:45]
	v_mfma_f32_16x16x32_bf16 v[34:37], v[152:155], v[184:187], v[34:37]
	v_mfma_f32_16x16x32_bf16 v[26:29], v[136:139], v[192:195], v[26:29]
	v_mfma_f32_16x16x32_bf16 v[18:21], v[152:155], v[192:195], v[18:21]
	v_mfma_f32_16x16x32_bf16 v[10:13], v[136:139], v[200:203], v[10:13]
	v_mfma_f32_16x16x32_bf16 v[2:5], v[152:155], v[200:203], v[2:5]
	v_mfma_f32_16x16x32_bf16 v[58:61], v[148:151], v[180:183], v[58:61]
	v_mfma_f32_16x16x32_bf16 v[50:53], v[156:159], v[180:183], v[50:53]
	v_mfma_f32_16x16x32_bf16 v[42:45], v[148:151], v[188:191], v[42:45]
	v_mfma_f32_16x16x32_bf16 v[34:37], v[156:159], v[188:191], v[34:37]
	v_mfma_f32_16x16x32_bf16 v[26:29], v[148:151], v[196:199], v[26:29]
	v_mfma_f32_16x16x32_bf16 v[18:21], v[156:159], v[196:199], v[18:21]
	v_mfma_f32_16x16x32_bf16 v[10:13], v[148:151], v[204:207], v[10:13]
	v_mfma_f32_16x16x32_bf16 v[2:5], v[156:159], v[204:207], v[2:5]
	v_mfma_f32_16x16x32_bf16 v[62:65], v[160:163], v[176:179], v[62:65]
	v_mfma_f32_16x16x32_bf16 v[54:57], v[168:171], v[176:179], v[54:57]
	v_mfma_f32_16x16x32_bf16 v[46:49], v[160:163], v[184:187], v[46:49]
	v_mfma_f32_16x16x32_bf16 v[38:41], v[168:171], v[184:187], v[38:41]
	v_mfma_f32_16x16x32_bf16 v[30:33], v[160:163], v[192:195], v[30:33]
	v_mfma_f32_16x16x32_bf16 v[22:25], v[168:171], v[192:195], v[22:25]
	v_mfma_f32_16x16x32_bf16 v[14:17], v[160:163], v[200:203], v[14:17]
	v_mfma_f32_16x16x32_bf16 v[6:9], v[168:171], v[200:203], v[6:9]
	v_mfma_f32_16x16x32_bf16 v[62:65], v[164:167], v[180:183], v[62:65]
	v_mfma_f32_16x16x32_bf16 v[54:57], v[172:175], v[180:183], v[54:57]
	v_mfma_f32_16x16x32_bf16 v[46:49], v[164:167], v[188:191], v[46:49]
	v_mfma_f32_16x16x32_bf16 v[38:41], v[172:175], v[188:191], v[38:41]
	v_mfma_f32_16x16x32_bf16 v[30:33], v[164:167], v[196:199], v[30:33]
	v_mfma_f32_16x16x32_bf16 v[22:25], v[172:175], v[196:199], v[22:25]
	v_mfma_f32_16x16x32_bf16 v[14:17], v[164:167], v[204:207], v[14:17]
	v_mfma_f32_16x16x32_bf16 v[6:9], v[172:175], v[204:207], v[6:9]
	s_barrier
	s_add_i32 s81, s81, 2
	s_add_u32 s79, s79, 0x100
	s_addc_u32 s80, s80, 0
	s_cmp_gt_u32 s81, 13
	s_mov_b64 s[50:51], s[0:1]
	s_cbranch_scc0 .LBB0_419
	s_and_b64 vcc, exec, s[24:25]
	s_cbranch_vccz .LBB0_422
	s_barrier

.LBB0_557:
	v_add_u32_e32 v134, 0x10000, v139
	ds_read_b128 v[142:145], v134
	ds_read_b128 v[146:149], v134 offset:1024
	ds_read_b128 v[150:153], v134 offset:2048
	ds_read_b128 v[154:157], v134 offset:3072
	v_add_u32_e32 v134, 0x14000, v139
	ds_read_b128 v[158:161], v134
	ds_read_b128 v[162:165], v134 offset:1024
	ds_read_b128 v[166:169], v134 offset:2048
	ds_read_b128 v[170:173], v134 offset:3072
	s_add_u32 s0, s44, 0x100
	s_addc_u32 s1, s45, 0
	s_cmp_eq_u32 s81, 12
	s_cselect_b32 s34, s15, s0
	s_cselect_b32 s35, s14, s1
	s_cselect_b32 s52, s27, s79
	s_cselect_b32 s53, s25, s80
	s_add_u32 s50, s34, 0x80
	s_addc_u32 s51, s35, 0
	ds_read_b128 v[174:177], v140
	ds_read_b128 v[178:181], v140 offset:1024
	ds_read_b128 v[182:185], v140 offset:2048
	ds_read_b128 v[186:189], v140 offset:3072
	ds_read_b128 v[190:193], v140 offset:4096
	ds_read_b128 v[194:197], v140 offset:5120
	ds_read_b128 v[198:201], v140 offset:6144
	ds_read_b128 v[202:205], v140 offset:7168
	s_add_u32 s84, s44, 0x40080
	s_addc_u32 s85, s45, 0
	s_mov_b32 s2, m0
	s_mov_b32 m0, s74
	s_nop 4
	global_load_lds_dwordx4 v1, s[84:85]
	s_mov_b32 m0, s2
	s_add_u32 s44, s44, 0x60080
	s_addc_u32 s45, s45, 0
	s_add_i32 s2, s43, 0xe000
	s_mov_b32 s3, m0
	s_mov_b32 m0, s2
	s_nop 4
	global_load_lds_dwordx4 v1, s[44:45]
	s_mov_b32 m0, s3
	s_waitcnt vmcnt(8)
	s_waitcnt lgkmcnt(0)
	s_barrier
	v_mfma_f32_16x16x32_bf16 v[122:125], v[142:145], v[174:177], v[122:125]
	v_mfma_f32_16x16x32_bf16 v[114:117], v[150:153], v[174:177], v[114:117]
	v_mfma_f32_16x16x32_bf16 v[106:109], v[142:145], v[182:185], v[106:109]
	v_mfma_f32_16x16x32_bf16 v[98:101], v[150:153], v[182:185], v[98:101]
	v_mfma_f32_16x16x32_bf16 v[90:93], v[142:145], v[190:193], v[90:93]
	v_mfma_f32_16x16x32_bf16 v[82:85], v[150:153], v[190:193], v[82:85]
	v_mfma_f32_16x16x32_bf16 v[74:77], v[142:145], v[198:201], v[74:77]
	v_mfma_f32_16x16x32_bf16 v[66:69], v[150:153], v[198:201], v[66:69]
	v_mfma_f32_16x16x32_bf16 v[122:125], v[146:149], v[178:181], v[122:125]
	v_mfma_f32_16x16x32_bf16 v[114:117], v[154:157], v[178:181], v[114:117]
	v_mfma_f32_16x16x32_bf16 v[106:109], v[146:149], v[186:189], v[106:109]
	v_mfma_f32_16x16x32_bf16 v[98:101], v[154:157], v[186:189], v[98:101]
	v_mfma_f32_16x16x32_bf16 v[90:93], v[146:149], v[194:197], v[90:93]
	v_mfma_f32_16x16x32_bf16 v[82:85], v[154:157], v[194:197], v[82:85]
	v_mfma_f32_16x16x32_bf16 v[74:77], v[146:149], v[202:205], v[74:77]
	v_mfma_f32_16x16x32_bf16 v[66:69], v[154:157], v[202:205], v[66:69]
	v_mfma_f32_16x16x32_bf16 v[126:129], v[158:161], v[174:177], v[126:129]
	v_mfma_f32_16x16x32_bf16 v[118:121], v[166:169], v[174:177], v[118:121]
	v_mfma_f32_16x16x32_bf16 v[110:113], v[158:161], v[182:185], v[110:113]
	v_mfma_f32_16x16x32_bf16 v[102:105], v[166:169], v[182:185], v[102:105]
	v_mfma_f32_16x16x32_bf16 v[94:97], v[158:161], v[190:193], v[94:97]
	v_mfma_f32_16x16x32_bf16 v[86:89], v[166:169], v[190:193], v[86:89]
	v_mfma_f32_16x16x32_bf16 v[78:81], v[158:161], v[198:201], v[78:81]
	v_mfma_f32_16x16x32_bf16 v[70:73], v[166:169], v[198:201], v[70:73]
	v_mfma_f32_16x16x32_bf16 v[126:129], v[162:165], v[178:181], v[126:129]
	v_mfma_f32_16x16x32_bf16 v[118:121], v[170:173], v[178:181], v[118:121]
	v_mfma_f32_16x16x32_bf16 v[110:113], v[162:165], v[186:189], v[110:113]
	v_mfma_f32_16x16x32_bf16 v[102:105], v[170:173], v[186:189], v[102:105]
	v_mfma_f32_16x16x32_bf16 v[94:97], v[162:165], v[194:197], v[94:97]
	v_mfma_f32_16x16x32_bf16 v[86:89], v[170:173], v[194:197], v[86:89]
	v_mfma_f32_16x16x32_bf16 v[78:81], v[162:165], v[202:205], v[78:81]
	v_mfma_f32_16x16x32_bf16 v[70:73], v[170:173], v[202:205], v[70:73]
	s_barrier
	s_add_u32 s44, s52, 0x20000
	ds_read_b128 v[174:177], v140 offset:16384
	ds_read_b128 v[178:181], v140 offset:17408
	ds_read_b128 v[182:185], v140 offset:18432
	ds_read_b128 v[186:189], v140 offset:19456
	ds_read_b128 v[190:193], v140 offset:20480
	ds_read_b128 v[194:197], v140 offset:21504
	ds_read_b128 v[198:201], v140 offset:22528
	ds_read_b128 v[202:205], v140 offset:23552
	s_mov_b32 s2, m0
	s_mov_b32 m0, s56
	s_nop 4
	global_load_lds_dwordx4 v136, s[52:53]
	s_mov_b32 m0, s2
	s_addc_u32 s45, s53, 0
	s_mov_b32 s2, m0
	s_mov_b32 m0, s57
	s_nop 4
	global_load_lds_dwordx4 v136, s[44:45]
	s_mov_b32 m0, s2
	s_add_u32 s44, s52, 0x40000
	s_addc_u32 s45, s53, 0
	s_mov_b32 s2, m0
	s_mov_b32 m0, s58
	s_nop 4
	global_load_lds_dwordx4 v136, s[44:45]
	s_mov_b32 m0, s2
	s_add_u32 s44, s52, 0x60000
	s_addc_u32 s45, s53, 0
	s_mov_b32 s2, m0
	s_mov_b32 m0, s59
	s_nop 4
	global_load_lds_dwordx4 v136, s[44:45]
	s_mov_b32 m0, s2
	s_add_u32 s44, s34, 0x20000
	s_mov_b32 s2, m0
	s_mov_b32 m0, s43
	s_nop 4
	global_load_lds_dwordx4 v1, s[34:35]
	s_mov_b32 m0, s2
	s_addc_u32 s45, s35, 0
	s_mov_b32 s2, m0
	s_mov_b32 m0, s60
	s_nop 4
	global_load_lds_dwordx4 v1, s[44:45]
	s_mov_b32 m0, s2
	s_waitcnt vmcnt(8)
	s_waitcnt lgkmcnt(0)
	s_barrier
	v_mfma_f32_16x16x32_bf16 v[58:61], v[142:145], v[174:177], v[58:61]
	v_mfma_f32_16x16x32_bf16 v[50:53], v[150:153], v[174:177], v[50:53]
	v_mfma_f32_16x16x32_bf16 v[42:45], v[142:145], v[182:185], v[42:45]
	v_mfma_f32_16x16x32_bf16 v[34:37], v[150:153], v[182:185], v[34:37]
	v_mfma_f32_16x16x32_bf16 v[26:29], v[142:145], v[190:193], v[26:29]
	v_mfma_f32_16x16x32_bf16 v[18:21], v[150:153], v[190:193], v[18:21]
	v_mfma_f32_16x16x32_bf16 v[10:13], v[142:145], v[198:201], v[10:13]
	v_mfma_f32_16x16x32_bf16 v[6:9], v[150:153], v[198:201], v[6:9]
	v_mfma_f32_16x16x32_bf16 v[58:61], v[146:149], v[178:181], v[58:61]
	v_mfma_f32_16x16x32_bf16 v[50:53], v[154:157], v[178:181], v[50:53]
	v_mfma_f32_16x16x32_bf16 v[42:45], v[146:149], v[186:189], v[42:45]
	v_mfma_f32_16x16x32_bf16 v[34:37], v[154:157], v[186:189], v[34:37]
	v_mfma_f32_16x16x32_bf16 v[26:29], v[146:149], v[194:197], v[26:29]
	v_mfma_f32_16x16x32_bf16 v[18:21], v[154:157], v[194:197], v[18:21]
	v_mfma_f32_16x16x32_bf16 v[10:13], v[146:149], v[202:205], v[10:13]
	v_mfma_f32_16x16x32_bf16 v[6:9], v[154:157], v[202:205], v[6:9]
	v_mfma_f32_16x16x32_bf16 v[62:65], v[158:161], v[174:177], v[62:65]
	v_mfma_f32_16x16x32_bf16 v[54:57], v[166:169], v[174:177], v[54:57]
	v_mfma_f32_16x16x32_bf16 v[46:49], v[158:161], v[182:185], v[46:49]
	v_mfma_f32_16x16x32_bf16 v[38:41], v[166:169], v[182:185], v[38:41]
	v_mfma_f32_16x16x32_bf16 v[30:33], v[158:161], v[190:193], v[30:33]
	v_mfma_f32_16x16x32_bf16 v[22:25], v[166:169], v[190:193], v[22:25]
	v_mfma_f32_16x16x32_bf16 v[14:17], v[158:161], v[198:201], v[14:17]
	v_mfma_f32_16x16x32_bf16 v[2:5], v[166:169], v[198:201], v[2:5]
	v_mfma_f32_16x16x32_bf16 v[62:65], v[162:165], v[178:181], v[62:65]
	v_mfma_f32_16x16x32_bf16 v[54:57], v[170:173], v[178:181], v[54:57]
	v_mfma_f32_16x16x32_bf16 v[46:49], v[162:165], v[186:189], v[46:49]
	v_mfma_f32_16x16x32_bf16 v[38:41], v[170:173], v[186:189], v[38:41]
	v_mfma_f32_16x16x32_bf16 v[30:33], v[162:165], v[194:197], v[30:33]
	v_mfma_f32_16x16x32_bf16 v[22:25], v[170:173], v[194:197], v[22:25]
	v_mfma_f32_16x16x32_bf16 v[14:17], v[162:165], v[202:205], v[14:17]
	v_mfma_f32_16x16x32_bf16 v[2:5], v[170:173], v[202:205], v[2:5]
	s_barrier
	v_add_u32_e32 v134, 0x18000, v139
	ds_read_b128 v[142:145], v134
	ds_read_b128 v[146:149], v134 offset:1024
	ds_read_b128 v[150:153], v134 offset:2048
	ds_read_b128 v[154:157], v134 offset:3072
	v_add_u32_e32 v134, 0x1c000, v139
	ds_read_b128 v[158:161], v134
	ds_read_b128 v[162:165], v134 offset:1024
	ds_read_b128 v[166:169], v134 offset:2048
	ds_read_b128 v[170:173], v134 offset:3072
	ds_read_b128 v[174:177], v140 offset:32768
	ds_read_b128 v[178:181], v140 offset:33792
	ds_read_b128 v[182:185], v140 offset:34816
	ds_read_b128 v[186:189], v140 offset:35840
	ds_read_b128 v[190:193], v140 offset:36864
	ds_read_b128 v[194:197], v140 offset:37888
	ds_read_b128 v[198:201], v140 offset:38912
	ds_read_b128 v[202:205], v140 offset:39936
	s_add_u32 s44, s34, 0x40000
	s_addc_u32 s45, s35, 0
	s_mov_b32 s2, m0
	s_mov_b32 m0, s61
	s_nop 4
	global_load_lds_dwordx4 v1, s[44:45]
	s_mov_b32 m0, s2
	s_add_u32 s44, s34, 0x60000
	s_addc_u32 s45, s35, 0
	s_mov_b32 s2, m0
	s_mov_b32 m0, s62
	s_nop 4
	global_load_lds_dwordx4 v1, s[44:45]
	s_mov_b32 m0, s2
	s_waitcnt vmcnt(8)
	s_waitcnt lgkmcnt(0)
	s_barrier
	v_mfma_f32_16x16x32_bf16 v[122:125], v[142:145], v[174:177], v[122:125]
	v_mfma_f32_16x16x32_bf16 v[114:117], v[150:153], v[174:177], v[114:117]
	v_mfma_f32_16x16x32_bf16 v[106:109], v[142:145], v[182:185], v[106:109]
	v_mfma_f32_16x16x32_bf16 v[98:101], v[150:153], v[182:185], v[98:101]
	v_mfma_f32_16x16x32_bf16 v[90:93], v[142:145], v[190:193], v[90:93]
	v_mfma_f32_16x16x32_bf16 v[82:85], v[150:153], v[190:193], v[82:85]
	v_mfma_f32_16x16x32_bf16 v[74:77], v[142:145], v[198:201], v[74:77]
	v_mfma_f32_16x16x32_bf16 v[66:69], v[150:153], v[198:201], v[66:69]
	v_mfma_f32_16x16x32_bf16 v[122:125], v[146:149], v[178:181], v[122:125]
	v_mfma_f32_16x16x32_bf16 v[114:117], v[154:157], v[178:181], v[114:117]
	v_mfma_f32_16x16x32_bf16 v[106:109], v[146:149], v[186:189], v[106:109]
	v_mfma_f32_16x16x32_bf16 v[98:101], v[154:157], v[186:189], v[98:101]
	v_mfma_f32_16x16x32_bf16 v[90:93], v[146:149], v[194:197], v[90:93]
	v_mfma_f32_16x16x32_bf16 v[82:85], v[154:157], v[194:197], v[82:85]
	v_mfma_f32_16x16x32_bf16 v[74:77], v[146:149], v[202:205], v[74:77]
	v_mfma_f32_16x16x32_bf16 v[66:69], v[154:157], v[202:205], v[66:69]
	v_mfma_f32_16x16x32_bf16 v[126:129], v[158:161], v[174:177], v[126:129]
	v_mfma_f32_16x16x32_bf16 v[118:121], v[166:169], v[174:177], v[118:121]
	v_mfma_f32_16x16x32_bf16 v[110:113], v[158:161], v[182:185], v[110:113]
	v_mfma_f32_16x16x32_bf16 v[102:105], v[166:169], v[182:185], v[102:105]
	v_mfma_f32_16x16x32_bf16 v[94:97], v[158:161], v[190:193], v[94:97]
	v_mfma_f32_16x16x32_bf16 v[86:89], v[166:169], v[190:193], v[86:89]
	v_mfma_f32_16x16x32_bf16 v[78:81], v[158:161], v[198:201], v[78:81]
	v_mfma_f32_16x16x32_bf16 v[70:73], v[166:169], v[198:201], v[70:73]
	v_mfma_f32_16x16x32_bf16 v[126:129], v[162:165], v[178:181], v[126:129]
	v_mfma_f32_16x16x32_bf16 v[118:121], v[170:173], v[178:181], v[118:121]
	v_mfma_f32_16x16x32_bf16 v[110:113], v[162:165], v[186:189], v[110:113]
	v_mfma_f32_16x16x32_bf16 v[102:105], v[170:173], v[186:189], v[102:105]
	v_mfma_f32_16x16x32_bf16 v[94:97], v[162:165], v[194:197], v[94:97]
	v_mfma_f32_16x16x32_bf16 v[86:89], v[170:173], v[194:197], v[86:89]
	v_mfma_f32_16x16x32_bf16 v[78:81], v[162:165], v[202:205], v[78:81]
	v_mfma_f32_16x16x32_bf16 v[70:73], v[170:173], v[202:205], v[70:73]
	s_barrier
	s_add_u32 s44, s52, 0x80
	s_addc_u32 s45, s53, 0
	ds_read_b128 v[174:177], v140 offset:49152
	ds_read_b128 v[178:181], v140 offset:50176
	ds_read_b128 v[182:185], v140 offset:51200
	ds_read_b128 v[186:189], v140 offset:52224
	ds_read_b128 v[190:193], v140 offset:53248
	ds_read_b128 v[194:197], v140 offset:54272
	ds_read_b128 v[198:201], v140 offset:55296
	ds_read_b128 v[202:205], v140 offset:56320
	s_mov_b32 s2, m0
	s_mov_b32 m0, s63
	s_nop 4
	global_load_lds_dwordx4 v136, s[44:45]
	s_mov_b32 m0, s2
	s_add_u32 s44, s52, 0x20080
	s_addc_u32 s45, s53, 0
	s_mov_b32 s2, m0
	s_mov_b32 m0, s64
	s_nop 4
	global_load_lds_dwordx4 v136, s[44:45]
	s_mov_b32 m0, s2
	s_add_u32 s44, s52, 0x40080
	s_addc_u32 s45, s53, 0
	s_mov_b32 s2, m0
	s_mov_b32 m0, s67
	s_nop 4
	global_load_lds_dwordx4 v136, s[44:45]
	s_mov_b32 m0, s2
	s_add_u32 s44, s52, 0x60080
	s_addc_u32 s45, s53, 0
	s_mov_b32 s2, m0
	s_mov_b32 m0, s73
	s_nop 4
	global_load_lds_dwordx4 v136, s[44:45]
	s_mov_b32 m0, s2
	s_add_u32 s34, s34, 0x20080
	s_mov_b32 s2, m0
	s_mov_b32 m0, s65
	s_nop 4
	global_load_lds_dwordx4 v1, s[50:51]
	s_mov_b32 m0, s2
	s_addc_u32 s35, s35, 0
	s_mov_b32 s2, m0
	s_mov_b32 m0, s66
	s_nop 4
	global_load_lds_dwordx4 v1, s[34:35]
	s_mov_b32 m0, s2
	s_waitcnt vmcnt(8)
	s_waitcnt lgkmcnt(0)
	s_barrier
	v_mfma_f32_16x16x32_bf16 v[58:61], v[142:145], v[174:177], v[58:61]
	v_mfma_f32_16x16x32_bf16 v[50:53], v[150:153], v[174:177], v[50:53]
	v_mfma_f32_16x16x32_bf16 v[42:45], v[142:145], v[182:185], v[42:45]
	v_mfma_f32_16x16x32_bf16 v[34:37], v[150:153], v[182:185], v[34:37]
	v_mfma_f32_16x16x32_bf16 v[26:29], v[142:145], v[190:193], v[26:29]
	v_mfma_f32_16x16x32_bf16 v[18:21], v[150:153], v[190:193], v[18:21]
	v_mfma_f32_16x16x32_bf16 v[10:13], v[142:145], v[198:201], v[10:13]
	v_mfma_f32_16x16x32_bf16 v[6:9], v[150:153], v[198:201], v[6:9]
	v_mfma_f32_16x16x32_bf16 v[58:61], v[146:149], v[178:181], v[58:61]
	v_mfma_f32_16x16x32_bf16 v[50:53], v[154:157], v[178:181], v[50:53]
	v_mfma_f32_16x16x32_bf16 v[42:45], v[146:149], v[186:189], v[42:45]
	v_mfma_f32_16x16x32_bf16 v[34:37], v[154:157], v[186:189], v[34:37]
	v_mfma_f32_16x16x32_bf16 v[26:29], v[146:149], v[194:197], v[26:29]
	v_mfma_f32_16x16x32_bf16 v[18:21], v[154:157], v[194:197], v[18:21]
	v_mfma_f32_16x16x32_bf16 v[10:13], v[146:149], v[202:205], v[10:13]
	v_mfma_f32_16x16x32_bf16 v[6:9], v[154:157], v[202:205], v[6:9]
	v_mfma_f32_16x16x32_bf16 v[62:65], v[158:161], v[174:177], v[62:65]
	v_mfma_f32_16x16x32_bf16 v[54:57], v[166:169], v[174:177], v[54:57]
	v_mfma_f32_16x16x32_bf16 v[46:49], v[158:161], v[182:185], v[46:49]
	v_mfma_f32_16x16x32_bf16 v[38:41], v[166:169], v[182:185], v[38:41]
	v_mfma_f32_16x16x32_bf16 v[30:33], v[158:161], v[190:193], v[30:33]
	v_mfma_f32_16x16x32_bf16 v[22:25], v[166:169], v[190:193], v[22:25]
	v_mfma_f32_16x16x32_bf16 v[14:17], v[158:161], v[198:201], v[14:17]
	v_mfma_f32_16x16x32_bf16 v[2:5], v[166:169], v[198:201], v[2:5]
	v_mfma_f32_16x16x32_bf16 v[62:65], v[162:165], v[178:181], v[62:65]
	v_mfma_f32_16x16x32_bf16 v[54:57], v[170:173], v[178:181], v[54:57]
	v_mfma_f32_16x16x32_bf16 v[46:49], v[162:165], v[186:189], v[46:49]
	v_mfma_f32_16x16x32_bf16 v[38:41], v[170:173], v[186:189], v[38:41]
	v_mfma_f32_16x16x32_bf16 v[30:33], v[162:165], v[194:197], v[30:33]
	v_mfma_f32_16x16x32_bf16 v[22:25], v[170:173], v[194:197], v[22:25]
	v_mfma_f32_16x16x32_bf16 v[14:17], v[162:165], v[202:205], v[14:17]
	v_mfma_f32_16x16x32_bf16 v[2:5], v[170:173], v[202:205], v[2:5]
	s_barrier
	s_add_i32 s81, s81, 2
	s_add_u32 s79, s79, 0x100
	s_addc_u32 s80, s80, 0
	s_cmp_gt_u32 s81, 13
	s_mov_b64 s[44:45], s[0:1]
	s_cbranch_scc0 .LBB0_557
	s_and_b64 vcc, exec, s[10:11]
	s_cbranch_vccz .LBB0_560
	s_barrier

.LBB0_752:
	v_add_u32_e32 v138, 0x10000, v143
	ds_read_b128 v[130:133], v138
	ds_read_b128 v[154:157], v138 offset:1024
	ds_read_b128 v[158:161], v138 offset:2048
	ds_read_b128 v[162:165], v138 offset:3072
	v_add_u32_e32 v138, 0x14000, v143
	ds_read_b128 v[166:169], v138
	ds_read_b128 v[170:173], v138 offset:1024
	ds_read_b128 v[174:177], v138 offset:2048
	ds_read_b128 v[178:181], v138 offset:3072
	s_add_u32 s0, s44, 0x100
	s_addc_u32 s1, s45, 0
	s_cmp_eq_u32 vcc_lo, 12
	s_cselect_b32 s34, s9, s0
	s_cselect_b32 s35, s7, s1
	s_cselect_b32 s52, s15, s27
	s_cselect_b32 s53, s14, s37
	s_add_u32 s50, s34, 0x80
	s_addc_u32 s51, s35, 0
	ds_read_b128 v[182:185], v145
	ds_read_b128 v[186:189], v145 offset:1024
	ds_read_b128 v[190:193], v145 offset:2048
	ds_read_b128 v[194:197], v145 offset:3072
	ds_read_b128 v[198:201], v145 offset:4096
	ds_read_b128 v[202:205], v145 offset:5120
	ds_read_b128 v[206:209], v145 offset:6144
	ds_read_b128 v[210:213], v145 offset:7168
	s_add_u32 s2, s44, 0x40080
	s_addc_u32 s3, s45, 0
	s_mov_b32 s12, m0
	s_mov_b32 m0, s96
	s_nop 4
	global_load_lds_dwordx4 v1, s[2:3]
	s_mov_b32 m0, s12
	s_add_u32 s2, s44, 0x60080
	s_addc_u32 s3, s45, 0
	s_add_i32 s12, s58, 0xe000
	s_mov_b32 s13, m0
	s_mov_b32 m0, s12
	s_nop 4
	global_load_lds_dwordx4 v1, s[2:3]
	s_mov_b32 m0, s13
	s_waitcnt vmcnt(8)
	s_waitcnt lgkmcnt(0)
	s_barrier
	v_mfma_f32_16x16x32_bf16 v[118:121], v[130:133], v[182:185], v[118:121]
	v_mfma_f32_16x16x32_bf16 v[114:117], v[158:161], v[182:185], v[114:117]
	v_mfma_f32_16x16x32_bf16 v[102:105], v[130:133], v[190:193], v[102:105]
	v_mfma_f32_16x16x32_bf16 v[98:101], v[158:161], v[190:193], v[98:101]
	v_mfma_f32_16x16x32_bf16 v[86:89], v[130:133], v[198:201], v[86:89]
	v_mfma_f32_16x16x32_bf16 v[82:85], v[158:161], v[198:201], v[82:85]
	v_mfma_f32_16x16x32_bf16 v[70:73], v[130:133], v[206:209], v[70:73]
	v_mfma_f32_16x16x32_bf16 v[66:69], v[158:161], v[206:209], v[66:69]
	v_mfma_f32_16x16x32_bf16 v[118:121], v[154:157], v[186:189], v[118:121]
	v_mfma_f32_16x16x32_bf16 v[114:117], v[162:165], v[186:189], v[114:117]
	v_mfma_f32_16x16x32_bf16 v[102:105], v[154:157], v[194:197], v[102:105]
	v_mfma_f32_16x16x32_bf16 v[98:101], v[162:165], v[194:197], v[98:101]
	v_mfma_f32_16x16x32_bf16 v[86:89], v[154:157], v[202:205], v[86:89]
	v_mfma_f32_16x16x32_bf16 v[82:85], v[162:165], v[202:205], v[82:85]
	v_mfma_f32_16x16x32_bf16 v[70:73], v[154:157], v[210:213], v[70:73]
	v_mfma_f32_16x16x32_bf16 v[66:69], v[162:165], v[210:213], v[66:69]
	v_mfma_f32_16x16x32_bf16 v[126:129], v[166:169], v[182:185], v[126:129]
	v_mfma_f32_16x16x32_bf16 v[122:125], v[174:177], v[182:185], v[122:125]
	v_mfma_f32_16x16x32_bf16 v[110:113], v[166:169], v[190:193], v[110:113]
	v_mfma_f32_16x16x32_bf16 v[106:109], v[174:177], v[190:193], v[106:109]
	v_mfma_f32_16x16x32_bf16 v[94:97], v[166:169], v[198:201], v[94:97]
	v_mfma_f32_16x16x32_bf16 v[90:93], v[174:177], v[198:201], v[90:93]
	v_mfma_f32_16x16x32_bf16 v[78:81], v[166:169], v[206:209], v[78:81]
	v_mfma_f32_16x16x32_bf16 v[74:77], v[174:177], v[206:209], v[74:77]
	v_mfma_f32_16x16x32_bf16 v[126:129], v[170:173], v[186:189], v[126:129]
	v_mfma_f32_16x16x32_bf16 v[122:125], v[178:181], v[186:189], v[122:125]
	v_mfma_f32_16x16x32_bf16 v[110:113], v[170:173], v[194:197], v[110:113]
	v_mfma_f32_16x16x32_bf16 v[106:109], v[178:181], v[194:197], v[106:109]
	v_mfma_f32_16x16x32_bf16 v[94:97], v[170:173], v[202:205], v[94:97]
	v_mfma_f32_16x16x32_bf16 v[90:93], v[178:181], v[202:205], v[90:93]
	v_mfma_f32_16x16x32_bf16 v[78:81], v[170:173], v[210:213], v[78:81]
	v_mfma_f32_16x16x32_bf16 v[74:77], v[178:181], v[210:213], v[74:77]
	s_barrier
	ds_read_b128 v[182:185], v145 offset:16384
	ds_read_b128 v[186:189], v145 offset:17408
	ds_read_b128 v[190:193], v145 offset:18432
	ds_read_b128 v[194:197], v145 offset:19456
	ds_read_b128 v[198:201], v145 offset:20480
	ds_read_b128 v[202:205], v145 offset:21504
	ds_read_b128 v[206:209], v145 offset:22528
	ds_read_b128 v[210:213], v145 offset:23552
	s_mov_b32 s2, m0
	s_mov_b32 m0, s60
	s_nop 4
	global_load_lds_dwordx4 v135, s[52:53]
	s_mov_b32 m0, s2
	s_add_u32 s2, s52, 0x20000
	s_addc_u32 s3, s53, 0
	s_mov_b32 s12, m0
	s_mov_b32 m0, s61
	s_nop 4
	global_load_lds_dwordx4 v135, s[2:3]
	s_mov_b32 m0, s12
	s_add_u32 s2, s52, 0x40000
	s_addc_u32 s3, s53, 0
	s_mov_b32 s12, m0
	s_mov_b32 m0, s62
	s_nop 4
	global_load_lds_dwordx4 v135, s[2:3]
	s_mov_b32 m0, s12
	s_add_u32 s2, s52, 0x60000
	s_addc_u32 s3, s53, 0
	s_mov_b32 s12, m0
	s_mov_b32 m0, s63
	s_nop 4
	global_load_lds_dwordx4 v135, s[2:3]
	s_mov_b32 m0, s12
	s_mov_b32 s2, m0
	s_mov_b32 m0, s58
	s_nop 4
	global_load_lds_dwordx4 v1, s[34:35]
	s_mov_b32 m0, s2
	s_add_u32 s2, s34, 0x20000
	s_addc_u32 s3, s35, 0
	s_mov_b32 s12, m0
	s_mov_b32 m0, s64
	s_nop 4
	global_load_lds_dwordx4 v1, s[2:3]
	s_mov_b32 m0, s12
	s_waitcnt vmcnt(8)
	s_waitcnt lgkmcnt(0)
	s_barrier
	v_mfma_f32_16x16x32_bf16 v[54:57], v[130:133], v[182:185], v[54:57]
	v_mfma_f32_16x16x32_bf16 v[50:53], v[158:161], v[182:185], v[50:53]
	v_mfma_f32_16x16x32_bf16 v[38:41], v[130:133], v[190:193], v[38:41]
	v_mfma_f32_16x16x32_bf16 v[34:37], v[158:161], v[190:193], v[34:37]
	v_mfma_f32_16x16x32_bf16 v[22:25], v[130:133], v[198:201], v[22:25]
	v_mfma_f32_16x16x32_bf16 v[18:21], v[158:161], v[198:201], v[18:21]
	v_mfma_f32_16x16x32_bf16 v[10:13], v[130:133], v[206:209], v[10:13]
	v_mfma_f32_16x16x32_bf16 v[6:9], v[158:161], v[206:209], v[6:9]
	v_mfma_f32_16x16x32_bf16 v[54:57], v[154:157], v[186:189], v[54:57]
	v_mfma_f32_16x16x32_bf16 v[50:53], v[162:165], v[186:189], v[50:53]
	v_mfma_f32_16x16x32_bf16 v[38:41], v[154:157], v[194:197], v[38:41]
	v_mfma_f32_16x16x32_bf16 v[34:37], v[162:165], v[194:197], v[34:37]
	v_mfma_f32_16x16x32_bf16 v[22:25], v[154:157], v[202:205], v[22:25]
	v_mfma_f32_16x16x32_bf16 v[18:21], v[162:165], v[202:205], v[18:21]
	v_mfma_f32_16x16x32_bf16 v[10:13], v[154:157], v[210:213], v[10:13]
	v_mfma_f32_16x16x32_bf16 v[6:9], v[162:165], v[210:213], v[6:9]
	v_mfma_f32_16x16x32_bf16 v[62:65], v[166:169], v[182:185], v[62:65]
	v_mfma_f32_16x16x32_bf16 v[58:61], v[174:177], v[182:185], v[58:61]
	v_mfma_f32_16x16x32_bf16 v[46:49], v[166:169], v[190:193], v[46:49]
	v_mfma_f32_16x16x32_bf16 v[42:45], v[174:177], v[190:193], v[42:45]
	v_mfma_f32_16x16x32_bf16 v[30:33], v[166:169], v[198:201], v[30:33]
	v_mfma_f32_16x16x32_bf16 v[26:29], v[174:177], v[198:201], v[26:29]
	v_mfma_f32_16x16x32_bf16 v[14:17], v[166:169], v[206:209], v[14:17]
	v_mfma_f32_16x16x32_bf16 v[2:5], v[174:177], v[206:209], v[2:5]
	v_mfma_f32_16x16x32_bf16 v[62:65], v[170:173], v[186:189], v[62:65]
	v_mfma_f32_16x16x32_bf16 v[58:61], v[178:181], v[186:189], v[58:61]
	v_mfma_f32_16x16x32_bf16 v[46:49], v[170:173], v[194:197], v[46:49]
	v_mfma_f32_16x16x32_bf16 v[42:45], v[178:181], v[194:197], v[42:45]
	v_mfma_f32_16x16x32_bf16 v[30:33], v[170:173], v[202:205], v[30:33]
	v_mfma_f32_16x16x32_bf16 v[26:29], v[178:181], v[202:205], v[26:29]
	v_mfma_f32_16x16x32_bf16 v[14:17], v[170:173], v[210:213], v[14:17]
	v_mfma_f32_16x16x32_bf16 v[2:5], v[178:181], v[210:213], v[2:5]
	s_barrier
	v_add_u32_e32 v138, 0x18000, v143
	ds_read_b128 v[130:133], v138
	ds_read_b128 v[154:157], v138 offset:1024
	ds_read_b128 v[158:161], v138 offset:2048
	ds_read_b128 v[162:165], v138 offset:3072
	v_add_u32_e32 v138, 0x1c000, v143
	ds_read_b128 v[166:169], v138
	ds_read_b128 v[170:173], v138 offset:1024
	ds_read_b128 v[174:177], v138 offset:2048
	ds_read_b128 v[178:181], v138 offset:3072
	ds_read_b128 v[182:185], v145 offset:32768
	ds_read_b128 v[186:189], v145 offset:33792
	ds_read_b128 v[190:193], v145 offset:34816
	ds_read_b128 v[194:197], v145 offset:35840
	ds_read_b128 v[198:201], v145 offset:36864
	ds_read_b128 v[202:205], v145 offset:37888
	ds_read_b128 v[206:209], v145 offset:38912
	ds_read_b128 v[210:213], v145 offset:39936
	s_add_u32 s2, s34, 0x40000
	s_addc_u32 s3, s35, 0
	s_mov_b32 s12, m0
	s_mov_b32 m0, s65
	s_nop 4
	global_load_lds_dwordx4 v1, s[2:3]
	s_mov_b32 m0, s12
	s_add_u32 s2, s34, 0x60000
	s_addc_u32 s3, s35, 0
	s_mov_b32 s12, m0
	s_mov_b32 m0, s66
	s_nop 4
	global_load_lds_dwordx4 v1, s[2:3]
	s_mov_b32 m0, s12
	s_waitcnt vmcnt(8)
	s_waitcnt lgkmcnt(0)
	s_barrier
	v_mfma_f32_16x16x32_bf16 v[118:121], v[130:133], v[182:185], v[118:121]
	v_mfma_f32_16x16x32_bf16 v[114:117], v[158:161], v[182:185], v[114:117]
	v_mfma_f32_16x16x32_bf16 v[102:105], v[130:133], v[190:193], v[102:105]
	v_mfma_f32_16x16x32_bf16 v[98:101], v[158:161], v[190:193], v[98:101]
	v_mfma_f32_16x16x32_bf16 v[86:89], v[130:133], v[198:201], v[86:89]
	v_mfma_f32_16x16x32_bf16 v[82:85], v[158:161], v[198:201], v[82:85]
	v_mfma_f32_16x16x32_bf16 v[70:73], v[130:133], v[206:209], v[70:73]
	v_mfma_f32_16x16x32_bf16 v[66:69], v[158:161], v[206:209], v[66:69]
	v_mfma_f32_16x16x32_bf16 v[118:121], v[154:157], v[186:189], v[118:121]
	v_mfma_f32_16x16x32_bf16 v[114:117], v[162:165], v[186:189], v[114:117]
	v_mfma_f32_16x16x32_bf16 v[102:105], v[154:157], v[194:197], v[102:105]
	v_mfma_f32_16x16x32_bf16 v[98:101], v[162:165], v[194:197], v[98:101]
	v_mfma_f32_16x16x32_bf16 v[86:89], v[154:157], v[202:205], v[86:89]
	v_mfma_f32_16x16x32_bf16 v[82:85], v[162:165], v[202:205], v[82:85]
	v_mfma_f32_16x16x32_bf16 v[70:73], v[154:157], v[210:213], v[70:73]
	v_mfma_f32_16x16x32_bf16 v[66:69], v[162:165], v[210:213], v[66:69]
	v_mfma_f32_16x16x32_bf16 v[126:129], v[166:169], v[182:185], v[126:129]
	v_mfma_f32_16x16x32_bf16 v[122:125], v[174:177], v[182:185], v[122:125]
	v_mfma_f32_16x16x32_bf16 v[110:113], v[166:169], v[190:193], v[110:113]
	v_mfma_f32_16x16x32_bf16 v[106:109], v[174:177], v[190:193], v[106:109]
	v_mfma_f32_16x16x32_bf16 v[94:97], v[166:169], v[198:201], v[94:97]
	v_mfma_f32_16x16x32_bf16 v[90:93], v[174:177], v[198:201], v[90:93]
	v_mfma_f32_16x16x32_bf16 v[78:81], v[166:169], v[206:209], v[78:81]
	v_mfma_f32_16x16x32_bf16 v[74:77], v[174:177], v[206:209], v[74:77]
	v_mfma_f32_16x16x32_bf16 v[126:129], v[170:173], v[186:189], v[126:129]
	v_mfma_f32_16x16x32_bf16 v[122:125], v[178:181], v[186:189], v[122:125]
	v_mfma_f32_16x16x32_bf16 v[110:113], v[170:173], v[194:197], v[110:113]
	v_mfma_f32_16x16x32_bf16 v[106:109], v[178:181], v[194:197], v[106:109]
	v_mfma_f32_16x16x32_bf16 v[94:97], v[170:173], v[202:205], v[94:97]
	v_mfma_f32_16x16x32_bf16 v[90:93], v[178:181], v[202:205], v[90:93]
	v_mfma_f32_16x16x32_bf16 v[78:81], v[170:173], v[210:213], v[78:81]
	v_mfma_f32_16x16x32_bf16 v[74:77], v[178:181], v[210:213], v[74:77]
	s_barrier
	s_add_u32 s2, s52, 0x80
	s_addc_u32 s3, s53, 0
	ds_read_b128 v[182:185], v145 offset:49152
	ds_read_b128 v[186:189], v145 offset:50176
	ds_read_b128 v[190:193], v145 offset:51200
	ds_read_b128 v[194:197], v145 offset:52224
	ds_read_b128 v[198:201], v145 offset:53248
	ds_read_b128 v[202:205], v145 offset:54272
	ds_read_b128 v[206:209], v145 offset:55296
	ds_read_b128 v[210:213], v145 offset:56320
	s_mov_b32 s12, m0
	s_mov_b32 m0, s90
	s_nop 4
	global_load_lds_dwordx4 v135, s[2:3]
	s_mov_b32 m0, s12
	s_add_u32 s2, s52, 0x20080
	s_addc_u32 s3, s53, 0
	s_mov_b32 s12, m0
	s_mov_b32 m0, s91
	s_nop 4
	global_load_lds_dwordx4 v135, s[2:3]
	s_mov_b32 m0, s12
	s_add_u32 s2, s52, 0x40080
	s_addc_u32 s3, s53, 0
	s_mov_b32 s12, m0
	s_mov_b32 m0, s94
	s_nop 4
	global_load_lds_dwordx4 v135, s[2:3]
	s_mov_b32 m0, s12
	s_add_u32 s2, s52, 0x60080
	s_addc_u32 s3, s53, 0
	s_mov_b32 s12, m0
	s_mov_b32 m0, s95
	s_nop 4
	global_load_lds_dwordx4 v135, s[2:3]
	s_mov_b32 m0, s12
	s_mov_b32 s2, m0
	s_mov_b32 m0, s92
	s_nop 4
	global_load_lds_dwordx4 v1, s[50:51]
	s_mov_b32 m0, s2
	s_add_u32 s2, s34, 0x20080
	s_addc_u32 s3, s35, 0
	s_mov_b32 s12, m0
	s_mov_b32 m0, s93
	s_nop 4
	global_load_lds_dwordx4 v1, s[2:3]
	s_mov_b32 m0, s12
	s_waitcnt vmcnt(8)
	s_waitcnt lgkmcnt(0)
	s_barrier
	v_mfma_f32_16x16x32_bf16 v[54:57], v[130:133], v[182:185], v[54:57]
	v_mfma_f32_16x16x32_bf16 v[50:53], v[158:161], v[182:185], v[50:53]
	v_mfma_f32_16x16x32_bf16 v[38:41], v[130:133], v[190:193], v[38:41]
	v_mfma_f32_16x16x32_bf16 v[34:37], v[158:161], v[190:193], v[34:37]
	v_mfma_f32_16x16x32_bf16 v[22:25], v[130:133], v[198:201], v[22:25]
	v_mfma_f32_16x16x32_bf16 v[18:21], v[158:161], v[198:201], v[18:21]
	v_mfma_f32_16x16x32_bf16 v[10:13], v[130:133], v[206:209], v[10:13]
	v_mfma_f32_16x16x32_bf16 v[6:9], v[158:161], v[206:209], v[6:9]
	v_mfma_f32_16x16x32_bf16 v[54:57], v[154:157], v[186:189], v[54:57]
	v_mfma_f32_16x16x32_bf16 v[50:53], v[162:165], v[186:189], v[50:53]
	v_mfma_f32_16x16x32_bf16 v[38:41], v[154:157], v[194:197], v[38:41]
	v_mfma_f32_16x16x32_bf16 v[34:37], v[162:165], v[194:197], v[34:37]
	v_mfma_f32_16x16x32_bf16 v[22:25], v[154:157], v[202:205], v[22:25]
	v_mfma_f32_16x16x32_bf16 v[18:21], v[162:165], v[202:205], v[18:21]
	v_mfma_f32_16x16x32_bf16 v[10:13], v[154:157], v[210:213], v[10:13]
	v_mfma_f32_16x16x32_bf16 v[6:9], v[162:165], v[210:213], v[6:9]
	v_mfma_f32_16x16x32_bf16 v[62:65], v[166:169], v[182:185], v[62:65]
	v_mfma_f32_16x16x32_bf16 v[58:61], v[174:177], v[182:185], v[58:61]
	v_mfma_f32_16x16x32_bf16 v[46:49], v[166:169], v[190:193], v[46:49]
	v_mfma_f32_16x16x32_bf16 v[42:45], v[174:177], v[190:193], v[42:45]
	v_mfma_f32_16x16x32_bf16 v[30:33], v[166:169], v[198:201], v[30:33]
	v_mfma_f32_16x16x32_bf16 v[26:29], v[174:177], v[198:201], v[26:29]
	v_mfma_f32_16x16x32_bf16 v[14:17], v[166:169], v[206:209], v[14:17]
	v_mfma_f32_16x16x32_bf16 v[2:5], v[174:177], v[206:209], v[2:5]
	v_mfma_f32_16x16x32_bf16 v[62:65], v[170:173], v[186:189], v[62:65]
	v_mfma_f32_16x16x32_bf16 v[58:61], v[178:181], v[186:189], v[58:61]
	v_mfma_f32_16x16x32_bf16 v[46:49], v[170:173], v[194:197], v[46:49]
	v_mfma_f32_16x16x32_bf16 v[42:45], v[178:181], v[194:197], v[42:45]
	v_mfma_f32_16x16x32_bf16 v[30:33], v[170:173], v[202:205], v[30:33]
	v_mfma_f32_16x16x32_bf16 v[26:29], v[178:181], v[202:205], v[26:29]
	v_mfma_f32_16x16x32_bf16 v[14:17], v[170:173], v[210:213], v[14:17]
	v_mfma_f32_16x16x32_bf16 v[2:5], v[178:181], v[210:213], v[2:5]
	s_barrier
	s_add_i32 vcc_lo, vcc_lo, 2
	s_add_u32 s27, s27, 0x100
	s_addc_u32 s37, s37, 0
	s_cmp_gt_u32 vcc_lo, 13
	s_mov_b64 s[44:45], s[0:1]
	s_cbranch_scc0 .LBB0_752
	s_and_b64 vcc, exec, s[24:25]
	s_cbranch_vccz .LBB0_755
	s_barrier

.LBB0_800:
	v_add_u32_e32 v134, 0x10000, v139
	ds_read_b128 v[142:145], v134
	ds_read_b128 v[146:149], v134 offset:1024
	ds_read_b128 v[150:153], v134 offset:2048
	ds_read_b128 v[154:157], v134 offset:3072
	v_add_u32_e32 v134, 0x14000, v139
	ds_read_b128 v[158:161], v134
	ds_read_b128 v[162:165], v134 offset:1024
	ds_read_b128 v[166:169], v134 offset:2048
	ds_read_b128 v[170:173], v134 offset:3072
	s_add_u32 s0, s42, 0x100
	s_addc_u32 s1, s43, 0
	s_cmp_eq_u32 s88, 12
	s_cselect_b32 s34, s15, s0
	s_cselect_b32 s35, s14, s1
	s_cselect_b32 s50, s25, s86
	s_cselect_b32 s51, s11, s87
	s_add_u32 s44, s34, 0x80
	s_addc_u32 s45, s35, 0
	ds_read_b128 v[174:177], v140
	ds_read_b128 v[178:181], v140 offset:1024
	ds_read_b128 v[182:185], v140 offset:2048
	ds_read_b128 v[186:189], v140 offset:3072
	ds_read_b128 v[190:193], v140 offset:4096
	ds_read_b128 v[194:197], v140 offset:5120
	ds_read_b128 v[198:201], v140 offset:6144
	ds_read_b128 v[202:205], v140 offset:7168
	s_add_u32 s2, s42, 0x40080
	s_addc_u32 s3, s43, 0
	s_mov_b32 s12, m0
	s_mov_b32 m0, s67
	s_nop 4
	global_load_lds_dwordx4 v1, s[2:3]
	s_mov_b32 m0, s12
	s_add_u32 s2, s42, 0x60080
	s_addc_u32 s3, s43, 0
	s_add_i32 s12, s39, 0xe000
	s_mov_b32 s13, m0
	s_mov_b32 m0, s12
	s_nop 4
	global_load_lds_dwordx4 v1, s[2:3]
	s_mov_b32 m0, s13
	s_waitcnt vmcnt(8)
	s_waitcnt lgkmcnt(0)
	s_barrier
	v_mfma_f32_16x16x32_bf16 v[122:125], v[142:145], v[174:177], v[122:125]
	v_mfma_f32_16x16x32_bf16 v[114:117], v[150:153], v[174:177], v[114:117]
	v_mfma_f32_16x16x32_bf16 v[106:109], v[142:145], v[182:185], v[106:109]
	v_mfma_f32_16x16x32_bf16 v[98:101], v[150:153], v[182:185], v[98:101]
	v_mfma_f32_16x16x32_bf16 v[90:93], v[142:145], v[190:193], v[90:93]
	v_mfma_f32_16x16x32_bf16 v[82:85], v[150:153], v[190:193], v[82:85]
	v_mfma_f32_16x16x32_bf16 v[74:77], v[142:145], v[198:201], v[74:77]
	v_mfma_f32_16x16x32_bf16 v[66:69], v[150:153], v[198:201], v[66:69]
	v_mfma_f32_16x16x32_bf16 v[122:125], v[146:149], v[178:181], v[122:125]
	v_mfma_f32_16x16x32_bf16 v[114:117], v[154:157], v[178:181], v[114:117]
	v_mfma_f32_16x16x32_bf16 v[106:109], v[146:149], v[186:189], v[106:109]
	v_mfma_f32_16x16x32_bf16 v[98:101], v[154:157], v[186:189], v[98:101]
	v_mfma_f32_16x16x32_bf16 v[90:93], v[146:149], v[194:197], v[90:93]
	v_mfma_f32_16x16x32_bf16 v[82:85], v[154:157], v[194:197], v[82:85]
	v_mfma_f32_16x16x32_bf16 v[74:77], v[146:149], v[202:205], v[74:77]
	v_mfma_f32_16x16x32_bf16 v[66:69], v[154:157], v[202:205], v[66:69]
	v_mfma_f32_16x16x32_bf16 v[126:129], v[158:161], v[174:177], v[126:129]
	v_mfma_f32_16x16x32_bf16 v[118:121], v[166:169], v[174:177], v[118:121]
	v_mfma_f32_16x16x32_bf16 v[110:113], v[158:161], v[182:185], v[110:113]
	v_mfma_f32_16x16x32_bf16 v[102:105], v[166:169], v[182:185], v[102:105]
	v_mfma_f32_16x16x32_bf16 v[94:97], v[158:161], v[190:193], v[94:97]
	v_mfma_f32_16x16x32_bf16 v[86:89], v[166:169], v[190:193], v[86:89]
	v_mfma_f32_16x16x32_bf16 v[78:81], v[158:161], v[198:201], v[78:81]
	v_mfma_f32_16x16x32_bf16 v[70:73], v[166:169], v[198:201], v[70:73]
	v_mfma_f32_16x16x32_bf16 v[126:129], v[162:165], v[178:181], v[126:129]
	v_mfma_f32_16x16x32_bf16 v[118:121], v[170:173], v[178:181], v[118:121]
	v_mfma_f32_16x16x32_bf16 v[110:113], v[162:165], v[186:189], v[110:113]
	v_mfma_f32_16x16x32_bf16 v[102:105], v[170:173], v[186:189], v[102:105]
	v_mfma_f32_16x16x32_bf16 v[94:97], v[162:165], v[194:197], v[94:97]
	v_mfma_f32_16x16x32_bf16 v[86:89], v[170:173], v[194:197], v[86:89]
	v_mfma_f32_16x16x32_bf16 v[78:81], v[162:165], v[202:205], v[78:81]
	v_mfma_f32_16x16x32_bf16 v[70:73], v[170:173], v[202:205], v[70:73]
	s_barrier
	ds_read_b128 v[174:177], v140 offset:16384
	ds_read_b128 v[178:181], v140 offset:17408
	ds_read_b128 v[182:185], v140 offset:18432
	ds_read_b128 v[186:189], v140 offset:19456
	ds_read_b128 v[190:193], v140 offset:20480
	ds_read_b128 v[194:197], v140 offset:21504
	ds_read_b128 v[198:201], v140 offset:22528
	ds_read_b128 v[202:205], v140 offset:23552
	s_mov_b32 s2, m0
	s_mov_b32 m0, s54
	s_nop 4
	global_load_lds_dwordx4 v136, s[50:51]
	s_mov_b32 m0, s2
	s_add_u32 s2, s50, 0x20000
	s_addc_u32 s3, s51, 0
	s_mov_b32 s12, m0
	s_mov_b32 m0, s55
	s_nop 4
	global_load_lds_dwordx4 v136, s[2:3]
	s_mov_b32 m0, s12
	s_add_u32 s2, s50, 0x40000
	s_addc_u32 s3, s51, 0
	s_mov_b32 s12, m0
	s_mov_b32 m0, s56
	s_nop 4
	global_load_lds_dwordx4 v136, s[2:3]
	s_mov_b32 m0, s12
	s_add_u32 s2, s50, 0x60000
	s_addc_u32 s3, s51, 0
	s_mov_b32 s12, m0
	s_mov_b32 m0, s57
	s_nop 4
	global_load_lds_dwordx4 v136, s[2:3]
	s_mov_b32 m0, s12
	s_mov_b32 s2, m0
	s_mov_b32 m0, s39
	s_nop 4
	global_load_lds_dwordx4 v1, s[34:35]
	s_mov_b32 m0, s2
	s_add_u32 s2, s34, 0x20000
	s_addc_u32 s3, s35, 0
	s_mov_b32 s12, m0
	s_mov_b32 m0, s58
	s_nop 4
	global_load_lds_dwordx4 v1, s[2:3]
	s_mov_b32 m0, s12
	s_waitcnt vmcnt(8)
	s_waitcnt lgkmcnt(0)
	s_barrier
	v_mfma_f32_16x16x32_bf16 v[58:61], v[142:145], v[174:177], v[58:61]
	v_mfma_f32_16x16x32_bf16 v[50:53], v[150:153], v[174:177], v[50:53]
	v_mfma_f32_16x16x32_bf16 v[42:45], v[142:145], v[182:185], v[42:45]
	v_mfma_f32_16x16x32_bf16 v[34:37], v[150:153], v[182:185], v[34:37]
	v_mfma_f32_16x16x32_bf16 v[26:29], v[142:145], v[190:193], v[26:29]
	v_mfma_f32_16x16x32_bf16 v[18:21], v[150:153], v[190:193], v[18:21]
	v_mfma_f32_16x16x32_bf16 v[10:13], v[142:145], v[198:201], v[10:13]
	v_mfma_f32_16x16x32_bf16 v[6:9], v[150:153], v[198:201], v[6:9]
	v_mfma_f32_16x16x32_bf16 v[58:61], v[146:149], v[178:181], v[58:61]
	v_mfma_f32_16x16x32_bf16 v[50:53], v[154:157], v[178:181], v[50:53]
	v_mfma_f32_16x16x32_bf16 v[42:45], v[146:149], v[186:189], v[42:45]
	v_mfma_f32_16x16x32_bf16 v[34:37], v[154:157], v[186:189], v[34:37]
	v_mfma_f32_16x16x32_bf16 v[26:29], v[146:149], v[194:197], v[26:29]
	v_mfma_f32_16x16x32_bf16 v[18:21], v[154:157], v[194:197], v[18:21]
	v_mfma_f32_16x16x32_bf16 v[10:13], v[146:149], v[202:205], v[10:13]
	v_mfma_f32_16x16x32_bf16 v[6:9], v[154:157], v[202:205], v[6:9]
	v_mfma_f32_16x16x32_bf16 v[62:65], v[158:161], v[174:177], v[62:65]
	v_mfma_f32_16x16x32_bf16 v[54:57], v[166:169], v[174:177], v[54:57]
	v_mfma_f32_16x16x32_bf16 v[46:49], v[158:161], v[182:185], v[46:49]
	v_mfma_f32_16x16x32_bf16 v[38:41], v[166:169], v[182:185], v[38:41]
	v_mfma_f32_16x16x32_bf16 v[30:33], v[158:161], v[190:193], v[30:33]
	v_mfma_f32_16x16x32_bf16 v[22:25], v[166:169], v[190:193], v[22:25]
	v_mfma_f32_16x16x32_bf16 v[14:17], v[158:161], v[198:201], v[14:17]
	v_mfma_f32_16x16x32_bf16 v[2:5], v[166:169], v[198:201], v[2:5]
	v_mfma_f32_16x16x32_bf16 v[62:65], v[162:165], v[178:181], v[62:65]
	v_mfma_f32_16x16x32_bf16 v[54:57], v[170:173], v[178:181], v[54:57]
	v_mfma_f32_16x16x32_bf16 v[46:49], v[162:165], v[186:189], v[46:49]
	v_mfma_f32_16x16x32_bf16 v[38:41], v[170:173], v[186:189], v[38:41]
	v_mfma_f32_16x16x32_bf16 v[30:33], v[162:165], v[194:197], v[30:33]
	v_mfma_f32_16x16x32_bf16 v[22:25], v[170:173], v[194:197], v[22:25]
	v_mfma_f32_16x16x32_bf16 v[14:17], v[162:165], v[202:205], v[14:17]
	v_mfma_f32_16x16x32_bf16 v[2:5], v[170:173], v[202:205], v[2:5]
	s_barrier
	v_add_u32_e32 v134, 0x18000, v139
	ds_read_b128 v[142:145], v134
	ds_read_b128 v[146:149], v134 offset:1024
	ds_read_b128 v[150:153], v134 offset:2048
	ds_read_b128 v[154:157], v134 offset:3072
	v_add_u32_e32 v134, 0x1c000, v139
	ds_read_b128 v[158:161], v134
	ds_read_b128 v[162:165], v134 offset:1024
	ds_read_b128 v[166:169], v134 offset:2048
	ds_read_b128 v[170:173], v134 offset:3072
	ds_read_b128 v[174:177], v140 offset:32768
	ds_read_b128 v[178:181], v140 offset:33792
	ds_read_b128 v[182:185], v140 offset:34816
	ds_read_b128 v[186:189], v140 offset:35840
	ds_read_b128 v[190:193], v140 offset:36864
	ds_read_b128 v[194:197], v140 offset:37888
	ds_read_b128 v[198:201], v140 offset:38912
	ds_read_b128 v[202:205], v140 offset:39936
	s_add_u32 s2, s34, 0x40000
	s_addc_u32 s3, s35, 0
	s_mov_b32 s12, m0
	s_mov_b32 m0, s59
	s_nop 4
	global_load_lds_dwordx4 v1, s[2:3]
	s_mov_b32 m0, s12
	s_add_u32 s2, s34, 0x60000
	s_addc_u32 s3, s35, 0
	s_mov_b32 s12, m0
	s_mov_b32 m0, s60
	s_nop 4
	global_load_lds_dwordx4 v1, s[2:3]
	s_mov_b32 m0, s12
	s_waitcnt vmcnt(8)
	s_waitcnt lgkmcnt(0)
	s_barrier
	v_mfma_f32_16x16x32_bf16 v[122:125], v[142:145], v[174:177], v[122:125]
	v_mfma_f32_16x16x32_bf16 v[114:117], v[150:153], v[174:177], v[114:117]
	v_mfma_f32_16x16x32_bf16 v[106:109], v[142:145], v[182:185], v[106:109]
	v_mfma_f32_16x16x32_bf16 v[98:101], v[150:153], v[182:185], v[98:101]
	v_mfma_f32_16x16x32_bf16 v[90:93], v[142:145], v[190:193], v[90:93]
	v_mfma_f32_16x16x32_bf16 v[82:85], v[150:153], v[190:193], v[82:85]
	v_mfma_f32_16x16x32_bf16 v[74:77], v[142:145], v[198:201], v[74:77]
	v_mfma_f32_16x16x32_bf16 v[66:69], v[150:153], v[198:201], v[66:69]
	v_mfma_f32_16x16x32_bf16 v[122:125], v[146:149], v[178:181], v[122:125]
	v_mfma_f32_16x16x32_bf16 v[114:117], v[154:157], v[178:181], v[114:117]
	v_mfma_f32_16x16x32_bf16 v[106:109], v[146:149], v[186:189], v[106:109]
	v_mfma_f32_16x16x32_bf16 v[98:101], v[154:157], v[186:189], v[98:101]
	v_mfma_f32_16x16x32_bf16 v[90:93], v[146:149], v[194:197], v[90:93]
	v_mfma_f32_16x16x32_bf16 v[82:85], v[154:157], v[194:197], v[82:85]
	v_mfma_f32_16x16x32_bf16 v[74:77], v[146:149], v[202:205], v[74:77]
	v_mfma_f32_16x16x32_bf16 v[66:69], v[154:157], v[202:205], v[66:69]
	v_mfma_f32_16x16x32_bf16 v[126:129], v[158:161], v[174:177], v[126:129]
	v_mfma_f32_16x16x32_bf16 v[118:121], v[166:169], v[174:177], v[118:121]
	v_mfma_f32_16x16x32_bf16 v[110:113], v[158:161], v[182:185], v[110:113]
	v_mfma_f32_16x16x32_bf16 v[102:105], v[166:169], v[182:185], v[102:105]
	v_mfma_f32_16x16x32_bf16 v[94:97], v[158:161], v[190:193], v[94:97]
	v_mfma_f32_16x16x32_bf16 v[86:89], v[166:169], v[190:193], v[86:89]
	v_mfma_f32_16x16x32_bf16 v[78:81], v[158:161], v[198:201], v[78:81]
	v_mfma_f32_16x16x32_bf16 v[70:73], v[166:169], v[198:201], v[70:73]
	v_mfma_f32_16x16x32_bf16 v[126:129], v[162:165], v[178:181], v[126:129]
	v_mfma_f32_16x16x32_bf16 v[118:121], v[170:173], v[178:181], v[118:121]
	v_mfma_f32_16x16x32_bf16 v[110:113], v[162:165], v[186:189], v[110:113]
	v_mfma_f32_16x16x32_bf16 v[102:105], v[170:173], v[186:189], v[102:105]
	v_mfma_f32_16x16x32_bf16 v[94:97], v[162:165], v[194:197], v[94:97]
	v_mfma_f32_16x16x32_bf16 v[86:89], v[170:173], v[194:197], v[86:89]
	v_mfma_f32_16x16x32_bf16 v[78:81], v[162:165], v[202:205], v[78:81]
	v_mfma_f32_16x16x32_bf16 v[70:73], v[170:173], v[202:205], v[70:73]
	s_barrier
	s_add_u32 s2, s50, 0x80
	s_addc_u32 s3, s51, 0
	ds_read_b128 v[174:177], v140 offset:49152
	ds_read_b128 v[178:181], v140 offset:50176
	ds_read_b128 v[182:185], v140 offset:51200
	ds_read_b128 v[186:189], v140 offset:52224
	ds_read_b128 v[190:193], v140 offset:53248
	ds_read_b128 v[194:197], v140 offset:54272
	ds_read_b128 v[198:201], v140 offset:55296
	ds_read_b128 v[202:205], v140 offset:56320
	s_mov_b32 s12, m0
	s_mov_b32 m0, s61
	s_nop 4
	global_load_lds_dwordx4 v136, s[2:3]
	s_mov_b32 m0, s12
	s_add_u32 s2, s50, 0x20080
	s_addc_u32 s3, s51, 0
	s_mov_b32 s12, m0
	s_mov_b32 m0, s62
	s_nop 4
	global_load_lds_dwordx4 v136, s[2:3]
	s_mov_b32 m0, s12
	s_add_u32 s2, s50, 0x40080
	s_addc_u32 s3, s51, 0
	s_mov_b32 s12, m0
	s_mov_b32 m0, s65
	s_nop 4
	global_load_lds_dwordx4 v136, s[2:3]
	s_mov_b32 m0, s12
	s_add_u32 s2, s50, 0x60080
	s_addc_u32 s3, s51, 0
	s_mov_b32 s12, m0
	s_mov_b32 m0, s66
	s_nop 4
	global_load_lds_dwordx4 v136, s[2:3]
	s_mov_b32 m0, s12
	s_mov_b32 s2, m0
	s_mov_b32 m0, s63
	s_nop 4
	global_load_lds_dwordx4 v1, s[44:45]
	s_mov_b32 m0, s2
	s_add_u32 s2, s34, 0x20080
	s_addc_u32 s3, s35, 0
	s_mov_b32 s12, m0
	s_mov_b32 m0, s64
	s_nop 4
	global_load_lds_dwordx4 v1, s[2:3]
	s_mov_b32 m0, s12
	s_waitcnt vmcnt(8)
	s_waitcnt lgkmcnt(0)
	s_barrier
	v_mfma_f32_16x16x32_bf16 v[58:61], v[142:145], v[174:177], v[58:61]
	v_mfma_f32_16x16x32_bf16 v[50:53], v[150:153], v[174:177], v[50:53]
	v_mfma_f32_16x16x32_bf16 v[42:45], v[142:145], v[182:185], v[42:45]
	v_mfma_f32_16x16x32_bf16 v[34:37], v[150:153], v[182:185], v[34:37]
	v_mfma_f32_16x16x32_bf16 v[26:29], v[142:145], v[190:193], v[26:29]
	v_mfma_f32_16x16x32_bf16 v[18:21], v[150:153], v[190:193], v[18:21]
	v_mfma_f32_16x16x32_bf16 v[10:13], v[142:145], v[198:201], v[10:13]
	v_mfma_f32_16x16x32_bf16 v[6:9], v[150:153], v[198:201], v[6:9]
	v_mfma_f32_16x16x32_bf16 v[58:61], v[146:149], v[178:181], v[58:61]
	v_mfma_f32_16x16x32_bf16 v[50:53], v[154:157], v[178:181], v[50:53]
	v_mfma_f32_16x16x32_bf16 v[42:45], v[146:149], v[186:189], v[42:45]
	v_mfma_f32_16x16x32_bf16 v[34:37], v[154:157], v[186:189], v[34:37]
	v_mfma_f32_16x16x32_bf16 v[26:29], v[146:149], v[194:197], v[26:29]
	v_mfma_f32_16x16x32_bf16 v[18:21], v[154:157], v[194:197], v[18:21]
	v_mfma_f32_16x16x32_bf16 v[10:13], v[146:149], v[202:205], v[10:13]
	v_mfma_f32_16x16x32_bf16 v[6:9], v[154:157], v[202:205], v[6:9]
	v_mfma_f32_16x16x32_bf16 v[62:65], v[158:161], v[174:177], v[62:65]
	v_mfma_f32_16x16x32_bf16 v[54:57], v[166:169], v[174:177], v[54:57]
	v_mfma_f32_16x16x32_bf16 v[46:49], v[158:161], v[182:185], v[46:49]
	v_mfma_f32_16x16x32_bf16 v[38:41], v[166:169], v[182:185], v[38:41]
	v_mfma_f32_16x16x32_bf16 v[30:33], v[158:161], v[190:193], v[30:33]
	v_mfma_f32_16x16x32_bf16 v[22:25], v[166:169], v[190:193], v[22:25]
	v_mfma_f32_16x16x32_bf16 v[14:17], v[158:161], v[198:201], v[14:17]
	v_mfma_f32_16x16x32_bf16 v[2:5], v[166:169], v[198:201], v[2:5]
	v_mfma_f32_16x16x32_bf16 v[62:65], v[162:165], v[178:181], v[62:65]
	v_mfma_f32_16x16x32_bf16 v[54:57], v[170:173], v[178:181], v[54:57]
	v_mfma_f32_16x16x32_bf16 v[46:49], v[162:165], v[186:189], v[46:49]
	v_mfma_f32_16x16x32_bf16 v[38:41], v[170:173], v[186:189], v[38:41]
	v_mfma_f32_16x16x32_bf16 v[30:33], v[162:165], v[194:197], v[30:33]
	v_mfma_f32_16x16x32_bf16 v[22:25], v[170:173], v[194:197], v[22:25]
	v_mfma_f32_16x16x32_bf16 v[14:17], v[162:165], v[202:205], v[14:17]
	v_mfma_f32_16x16x32_bf16 v[2:5], v[170:173], v[202:205], v[2:5]
	s_barrier
	s_add_i32 s88, s88, 2
	s_add_u32 s86, s86, 0x100
	s_addc_u32 s87, s87, 0
	s_cmp_gt_u32 s88, 13
	s_mov_b64 s[42:43], s[0:1]
	s_cbranch_scc0 .LBB0_800
	s_and_b64 vcc, exec, s[8:9]
	s_cbranch_vccz .LBB0_803
	s_barrier

.LBB0_988:
	v_add_u32_e32 v130, 0x10000, v150
	ds_read_b128 v[152:155], v130
	ds_read_b128 v[156:159], v130 offset:1024
	ds_read_b128 v[160:163], v130 offset:2048
	ds_read_b128 v[164:167], v130 offset:3072
	v_add_u32_e32 v130, 0x14000, v150
	ds_read_b128 v[168:171], v130
	ds_read_b128 v[172:175], v130 offset:1024
	ds_read_b128 v[176:179], v130 offset:2048
	ds_read_b128 v[180:183], v130 offset:3072
	s_add_u32 s0, s40, 0x100
	s_addc_u32 s1, s41, 0
	s_cmp_eq_u32 s88, 12
	s_cselect_b32 s34, s15, s0
	s_cselect_b32 s35, s14, s1
	s_cselect_b32 s44, s25, s86
	s_cselect_b32 s45, s11, s87
	s_add_u32 s42, s34, 0x80
	s_addc_u32 s43, s35, 0
	ds_read_b128 v[184:187], v151
	ds_read_b128 v[188:191], v151 offset:1024
	ds_read_b128 v[192:195], v151 offset:2048
	ds_read_b128 v[196:199], v151 offset:3072
	ds_read_b128 v[200:203], v151 offset:4096
	ds_read_b128 v[204:207], v151 offset:5120
	ds_read_b128 v[208:211], v151 offset:6144
	ds_read_b128 v[212:215], v151 offset:7168
	s_add_u32 s12, s40, 0x40080
	s_addc_u32 s13, s41, 0
	s_mov_b32 s89, m0
	s_mov_b32 m0, s82
	s_nop 4
	global_load_lds_dwordx4 v1, s[12:13]
	s_mov_b32 m0, s89
	s_add_u32 s12, s40, 0x60080
	s_addc_u32 s13, s41, 0
	s_add_i32 s40, s54, 0xe000
	s_mov_b32 s41, m0
	s_mov_b32 m0, s40
	s_nop 4
	global_load_lds_dwordx4 v1, s[12:13]
	s_mov_b32 m0, s41
	s_waitcnt vmcnt(8)
	s_waitcnt lgkmcnt(0)
	s_barrier
	v_mfma_f32_16x16x32_bf16 v[122:125], v[152:155], v[184:187], v[122:125]
	v_mfma_f32_16x16x32_bf16 v[114:117], v[160:163], v[184:187], v[114:117]
	v_mfma_f32_16x16x32_bf16 v[106:109], v[152:155], v[192:195], v[106:109]
	v_mfma_f32_16x16x32_bf16 v[98:101], v[160:163], v[192:195], v[98:101]
	v_mfma_f32_16x16x32_bf16 v[90:93], v[152:155], v[200:203], v[90:93]
	v_mfma_f32_16x16x32_bf16 v[82:85], v[160:163], v[200:203], v[82:85]
	v_mfma_f32_16x16x32_bf16 v[74:77], v[152:155], v[208:211], v[74:77]
	v_mfma_f32_16x16x32_bf16 v[66:69], v[160:163], v[208:211], v[66:69]
	v_mfma_f32_16x16x32_bf16 v[122:125], v[156:159], v[188:191], v[122:125]
	v_mfma_f32_16x16x32_bf16 v[114:117], v[164:167], v[188:191], v[114:117]
	v_mfma_f32_16x16x32_bf16 v[106:109], v[156:159], v[196:199], v[106:109]
	v_mfma_f32_16x16x32_bf16 v[98:101], v[164:167], v[196:199], v[98:101]
	v_mfma_f32_16x16x32_bf16 v[90:93], v[156:159], v[204:207], v[90:93]
	v_mfma_f32_16x16x32_bf16 v[82:85], v[164:167], v[204:207], v[82:85]
	v_mfma_f32_16x16x32_bf16 v[74:77], v[156:159], v[212:215], v[74:77]
	v_mfma_f32_16x16x32_bf16 v[66:69], v[164:167], v[212:215], v[66:69]
	v_mfma_f32_16x16x32_bf16 v[126:129], v[168:171], v[184:187], v[126:129]
	v_mfma_f32_16x16x32_bf16 v[118:121], v[176:179], v[184:187], v[118:121]
	v_mfma_f32_16x16x32_bf16 v[110:113], v[168:171], v[192:195], v[110:113]
	v_mfma_f32_16x16x32_bf16 v[102:105], v[176:179], v[192:195], v[102:105]
	v_mfma_f32_16x16x32_bf16 v[94:97], v[168:171], v[200:203], v[94:97]
	v_mfma_f32_16x16x32_bf16 v[86:89], v[176:179], v[200:203], v[86:89]
	v_mfma_f32_16x16x32_bf16 v[78:81], v[168:171], v[208:211], v[78:81]
	v_mfma_f32_16x16x32_bf16 v[70:73], v[176:179], v[208:211], v[70:73]
	v_mfma_f32_16x16x32_bf16 v[126:129], v[172:175], v[188:191], v[126:129]
	v_mfma_f32_16x16x32_bf16 v[118:121], v[180:183], v[188:191], v[118:121]
	v_mfma_f32_16x16x32_bf16 v[110:113], v[172:175], v[196:199], v[110:113]
	v_mfma_f32_16x16x32_bf16 v[102:105], v[180:183], v[196:199], v[102:105]
	v_mfma_f32_16x16x32_bf16 v[94:97], v[172:175], v[204:207], v[94:97]
	v_mfma_f32_16x16x32_bf16 v[86:89], v[180:183], v[204:207], v[86:89]
	v_mfma_f32_16x16x32_bf16 v[78:81], v[172:175], v[212:215], v[78:81]
	v_mfma_f32_16x16x32_bf16 v[70:73], v[180:183], v[212:215], v[70:73]
	s_barrier
	ds_read_b128 v[184:187], v151 offset:16384
	ds_read_b128 v[188:191], v151 offset:17408
	ds_read_b128 v[192:195], v151 offset:18432
	ds_read_b128 v[196:199], v151 offset:19456
	ds_read_b128 v[200:203], v151 offset:20480
	ds_read_b128 v[204:207], v151 offset:21504
	ds_read_b128 v[208:211], v151 offset:22528
	ds_read_b128 v[212:215], v151 offset:23552
	s_mov_b32 s12, m0
	s_mov_b32 m0, s56
	s_nop 4
	global_load_lds_dwordx4 v144, s[44:45]
	s_mov_b32 m0, s12
	s_add_u32 s12, s44, 0x20000
	s_addc_u32 s13, s45, 0
	s_mov_b32 s40, m0
	s_mov_b32 m0, s57
	s_nop 4
	global_load_lds_dwordx4 v144, s[12:13]
	s_mov_b32 m0, s40
	s_add_u32 s12, s44, 0x40000
	s_addc_u32 s13, s45, 0
	s_mov_b32 s40, m0
	s_mov_b32 m0, s58
	s_nop 4
	global_load_lds_dwordx4 v144, s[12:13]
	s_mov_b32 m0, s40
	s_add_u32 s12, s44, 0x60000
	s_addc_u32 s13, s45, 0
	s_mov_b32 s40, m0
	s_mov_b32 m0, s59
	s_nop 4
	global_load_lds_dwordx4 v144, s[12:13]
	s_mov_b32 m0, s40
	s_mov_b32 s12, m0
	s_mov_b32 m0, s54
	s_nop 4
	global_load_lds_dwordx4 v1, s[34:35]
	s_mov_b32 m0, s12
	s_add_u32 s12, s34, 0x20000
	s_addc_u32 s13, s35, 0
	s_mov_b32 s40, m0
	s_mov_b32 m0, s60
	s_nop 4
	global_load_lds_dwordx4 v1, s[12:13]
	s_mov_b32 m0, s40
	s_waitcnt vmcnt(8)
	s_waitcnt lgkmcnt(0)
	s_barrier
	v_mfma_f32_16x16x32_bf16 v[58:61], v[152:155], v[184:187], v[58:61]
	v_mfma_f32_16x16x32_bf16 v[50:53], v[160:163], v[184:187], v[50:53]
	v_mfma_f32_16x16x32_bf16 v[42:45], v[152:155], v[192:195], v[42:45]
	v_mfma_f32_16x16x32_bf16 v[34:37], v[160:163], v[192:195], v[34:37]
	v_mfma_f32_16x16x32_bf16 v[26:29], v[152:155], v[200:203], v[26:29]
	v_mfma_f32_16x16x32_bf16 v[18:21], v[160:163], v[200:203], v[18:21]
	v_mfma_f32_16x16x32_bf16 v[10:13], v[152:155], v[208:211], v[10:13]
	v_mfma_f32_16x16x32_bf16 v[6:9], v[160:163], v[208:211], v[6:9]
	v_mfma_f32_16x16x32_bf16 v[58:61], v[156:159], v[188:191], v[58:61]
	v_mfma_f32_16x16x32_bf16 v[50:53], v[164:167], v[188:191], v[50:53]
	v_mfma_f32_16x16x32_bf16 v[42:45], v[156:159], v[196:199], v[42:45]
	v_mfma_f32_16x16x32_bf16 v[34:37], v[164:167], v[196:199], v[34:37]
	v_mfma_f32_16x16x32_bf16 v[26:29], v[156:159], v[204:207], v[26:29]
	v_mfma_f32_16x16x32_bf16 v[18:21], v[164:167], v[204:207], v[18:21]
	v_mfma_f32_16x16x32_bf16 v[10:13], v[156:159], v[212:215], v[10:13]
	v_mfma_f32_16x16x32_bf16 v[6:9], v[164:167], v[212:215], v[6:9]
	v_mfma_f32_16x16x32_bf16 v[62:65], v[168:171], v[184:187], v[62:65]
	v_mfma_f32_16x16x32_bf16 v[54:57], v[176:179], v[184:187], v[54:57]
	v_mfma_f32_16x16x32_bf16 v[46:49], v[168:171], v[192:195], v[46:49]
	v_mfma_f32_16x16x32_bf16 v[38:41], v[176:179], v[192:195], v[38:41]
	v_mfma_f32_16x16x32_bf16 v[30:33], v[168:171], v[200:203], v[30:33]
	v_mfma_f32_16x16x32_bf16 v[22:25], v[176:179], v[200:203], v[22:25]
	v_mfma_f32_16x16x32_bf16 v[14:17], v[168:171], v[208:211], v[14:17]
	v_mfma_f32_16x16x32_bf16 v[2:5], v[176:179], v[208:211], v[2:5]
	v_mfma_f32_16x16x32_bf16 v[62:65], v[172:175], v[188:191], v[62:65]
	v_mfma_f32_16x16x32_bf16 v[54:57], v[180:183], v[188:191], v[54:57]
	v_mfma_f32_16x16x32_bf16 v[46:49], v[172:175], v[196:199], v[46:49]
	v_mfma_f32_16x16x32_bf16 v[38:41], v[180:183], v[196:199], v[38:41]
	v_mfma_f32_16x16x32_bf16 v[30:33], v[172:175], v[204:207], v[30:33]
	v_mfma_f32_16x16x32_bf16 v[22:25], v[180:183], v[204:207], v[22:25]
	v_mfma_f32_16x16x32_bf16 v[14:17], v[172:175], v[212:215], v[14:17]
	v_mfma_f32_16x16x32_bf16 v[2:5], v[180:183], v[212:215], v[2:5]
	s_barrier
	v_add_u32_e32 v130, 0x18000, v150
	ds_read_b128 v[152:155], v130
	ds_read_b128 v[156:159], v130 offset:1024
	ds_read_b128 v[160:163], v130 offset:2048
	ds_read_b128 v[164:167], v130 offset:3072
	v_add_u32_e32 v130, 0x1c000, v150
	ds_read_b128 v[168:171], v130
	ds_read_b128 v[172:175], v130 offset:1024
	ds_read_b128 v[176:179], v130 offset:2048
	ds_read_b128 v[180:183], v130 offset:3072
	ds_read_b128 v[184:187], v151 offset:32768
	ds_read_b128 v[188:191], v151 offset:33792
	ds_read_b128 v[192:195], v151 offset:34816
	ds_read_b128 v[196:199], v151 offset:35840
	ds_read_b128 v[200:203], v151 offset:36864
	ds_read_b128 v[204:207], v151 offset:37888
	ds_read_b128 v[208:211], v151 offset:38912
	ds_read_b128 v[212:215], v151 offset:39936
	s_add_u32 s12, s34, 0x40000
	s_addc_u32 s13, s35, 0
	s_mov_b32 s40, m0
	s_mov_b32 m0, s61
	s_nop 4
	global_load_lds_dwordx4 v1, s[12:13]
	s_mov_b32 m0, s40
	s_add_u32 s12, s34, 0x60000
	s_addc_u32 s13, s35, 0
	s_mov_b32 s40, m0
	s_mov_b32 m0, s62
	s_nop 4
	global_load_lds_dwordx4 v1, s[12:13]
	s_mov_b32 m0, s40
	s_waitcnt vmcnt(8)
	s_waitcnt lgkmcnt(0)
	s_barrier
	v_mfma_f32_16x16x32_bf16 v[122:125], v[152:155], v[184:187], v[122:125]
	v_mfma_f32_16x16x32_bf16 v[114:117], v[160:163], v[184:187], v[114:117]
	v_mfma_f32_16x16x32_bf16 v[106:109], v[152:155], v[192:195], v[106:109]
	v_mfma_f32_16x16x32_bf16 v[98:101], v[160:163], v[192:195], v[98:101]
	v_mfma_f32_16x16x32_bf16 v[90:93], v[152:155], v[200:203], v[90:93]
	v_mfma_f32_16x16x32_bf16 v[82:85], v[160:163], v[200:203], v[82:85]
	v_mfma_f32_16x16x32_bf16 v[74:77], v[152:155], v[208:211], v[74:77]
	v_mfma_f32_16x16x32_bf16 v[66:69], v[160:163], v[208:211], v[66:69]
	v_mfma_f32_16x16x32_bf16 v[122:125], v[156:159], v[188:191], v[122:125]
	v_mfma_f32_16x16x32_bf16 v[114:117], v[164:167], v[188:191], v[114:117]
	v_mfma_f32_16x16x32_bf16 v[106:109], v[156:159], v[196:199], v[106:109]
	v_mfma_f32_16x16x32_bf16 v[98:101], v[164:167], v[196:199], v[98:101]
	v_mfma_f32_16x16x32_bf16 v[90:93], v[156:159], v[204:207], v[90:93]
	v_mfma_f32_16x16x32_bf16 v[82:85], v[164:167], v[204:207], v[82:85]
	v_mfma_f32_16x16x32_bf16 v[74:77], v[156:159], v[212:215], v[74:77]
	v_mfma_f32_16x16x32_bf16 v[66:69], v[164:167], v[212:215], v[66:69]
	v_mfma_f32_16x16x32_bf16 v[126:129], v[168:171], v[184:187], v[126:129]
	v_mfma_f32_16x16x32_bf16 v[118:121], v[176:179], v[184:187], v[118:121]
	v_mfma_f32_16x16x32_bf16 v[110:113], v[168:171], v[192:195], v[110:113]
	v_mfma_f32_16x16x32_bf16 v[102:105], v[176:179], v[192:195], v[102:105]
	v_mfma_f32_16x16x32_bf16 v[94:97], v[168:171], v[200:203], v[94:97]
	v_mfma_f32_16x16x32_bf16 v[86:89], v[176:179], v[200:203], v[86:89]
	v_mfma_f32_16x16x32_bf16 v[78:81], v[168:171], v[208:211], v[78:81]
	v_mfma_f32_16x16x32_bf16 v[70:73], v[176:179], v[208:211], v[70:73]
	v_mfma_f32_16x16x32_bf16 v[126:129], v[172:175], v[188:191], v[126:129]
	v_mfma_f32_16x16x32_bf16 v[118:121], v[180:183], v[188:191], v[118:121]
	v_mfma_f32_16x16x32_bf16 v[110:113], v[172:175], v[196:199], v[110:113]
	v_mfma_f32_16x16x32_bf16 v[102:105], v[180:183], v[196:199], v[102:105]
	v_mfma_f32_16x16x32_bf16 v[94:97], v[172:175], v[204:207], v[94:97]
	v_mfma_f32_16x16x32_bf16 v[86:89], v[180:183], v[204:207], v[86:89]
	v_mfma_f32_16x16x32_bf16 v[78:81], v[172:175], v[212:215], v[78:81]
	v_mfma_f32_16x16x32_bf16 v[70:73], v[180:183], v[212:215], v[70:73]
	s_barrier
	s_add_u32 s12, s44, 0x80
	s_addc_u32 s13, s45, 0
	ds_read_b128 v[184:187], v151 offset:49152
	ds_read_b128 v[188:191], v151 offset:50176
	ds_read_b128 v[192:195], v151 offset:51200
	ds_read_b128 v[196:199], v151 offset:52224
	ds_read_b128 v[200:203], v151 offset:53248
	ds_read_b128 v[204:207], v151 offset:54272
	ds_read_b128 v[208:211], v151 offset:55296
	ds_read_b128 v[212:215], v151 offset:56320
	s_mov_b32 s40, m0
	s_mov_b32 m0, s63
	s_nop 4
	global_load_lds_dwordx4 v144, s[12:13]
	s_mov_b32 m0, s40
	s_add_u32 s12, s44, 0x20080
	s_addc_u32 s13, s45, 0
	s_mov_b32 s40, m0
	s_mov_b32 m0, s64
	s_nop 4
	global_load_lds_dwordx4 v144, s[12:13]
	s_mov_b32 m0, s40
	s_add_u32 s12, s44, 0x40080
	s_addc_u32 s13, s45, 0
	s_mov_b32 s40, m0
	s_mov_b32 m0, s67
	s_nop 4
	global_load_lds_dwordx4 v144, s[12:13]
	s_mov_b32 m0, s40
	s_add_u32 s12, s44, 0x60080
	s_addc_u32 s13, s45, 0
	s_mov_b32 s40, m0
	s_mov_b32 m0, s73
	s_nop 4
	global_load_lds_dwordx4 v144, s[12:13]
	s_mov_b32 m0, s40
	s_mov_b32 s12, m0
	s_mov_b32 m0, s65
	s_nop 4
	global_load_lds_dwordx4 v1, s[42:43]
	s_mov_b32 m0, s12
	s_add_u32 s12, s34, 0x20080
	s_addc_u32 s13, s35, 0
	s_mov_b32 s34, m0
	s_mov_b32 m0, s66
	s_nop 4
	global_load_lds_dwordx4 v1, s[12:13]
	s_mov_b32 m0, s34
	s_waitcnt vmcnt(8)
	s_waitcnt lgkmcnt(0)
	s_barrier
	v_mfma_f32_16x16x32_bf16 v[58:61], v[152:155], v[184:187], v[58:61]
	v_mfma_f32_16x16x32_bf16 v[50:53], v[160:163], v[184:187], v[50:53]
	v_mfma_f32_16x16x32_bf16 v[42:45], v[152:155], v[192:195], v[42:45]
	v_mfma_f32_16x16x32_bf16 v[34:37], v[160:163], v[192:195], v[34:37]
	v_mfma_f32_16x16x32_bf16 v[26:29], v[152:155], v[200:203], v[26:29]
	v_mfma_f32_16x16x32_bf16 v[18:21], v[160:163], v[200:203], v[18:21]
	v_mfma_f32_16x16x32_bf16 v[10:13], v[152:155], v[208:211], v[10:13]
	v_mfma_f32_16x16x32_bf16 v[6:9], v[160:163], v[208:211], v[6:9]
	v_mfma_f32_16x16x32_bf16 v[58:61], v[156:159], v[188:191], v[58:61]
	v_mfma_f32_16x16x32_bf16 v[50:53], v[164:167], v[188:191], v[50:53]
	v_mfma_f32_16x16x32_bf16 v[42:45], v[156:159], v[196:199], v[42:45]
	v_mfma_f32_16x16x32_bf16 v[34:37], v[164:167], v[196:199], v[34:37]
	v_mfma_f32_16x16x32_bf16 v[26:29], v[156:159], v[204:207], v[26:29]
	v_mfma_f32_16x16x32_bf16 v[18:21], v[164:167], v[204:207], v[18:21]
	v_mfma_f32_16x16x32_bf16 v[10:13], v[156:159], v[212:215], v[10:13]
	v_mfma_f32_16x16x32_bf16 v[6:9], v[164:167], v[212:215], v[6:9]
	v_mfma_f32_16x16x32_bf16 v[62:65], v[168:171], v[184:187], v[62:65]
	v_mfma_f32_16x16x32_bf16 v[54:57], v[176:179], v[184:187], v[54:57]
	v_mfma_f32_16x16x32_bf16 v[46:49], v[168:171], v[192:195], v[46:49]
	v_mfma_f32_16x16x32_bf16 v[38:41], v[176:179], v[192:195], v[38:41]
	v_mfma_f32_16x16x32_bf16 v[30:33], v[168:171], v[200:203], v[30:33]
	v_mfma_f32_16x16x32_bf16 v[22:25], v[176:179], v[200:203], v[22:25]
	v_mfma_f32_16x16x32_bf16 v[14:17], v[168:171], v[208:211], v[14:17]
	v_mfma_f32_16x16x32_bf16 v[2:5], v[176:179], v[208:211], v[2:5]
	v_mfma_f32_16x16x32_bf16 v[62:65], v[172:175], v[188:191], v[62:65]
	v_mfma_f32_16x16x32_bf16 v[54:57], v[180:183], v[188:191], v[54:57]
	v_mfma_f32_16x16x32_bf16 v[46:49], v[172:175], v[196:199], v[46:49]
	v_mfma_f32_16x16x32_bf16 v[38:41], v[180:183], v[196:199], v[38:41]
	v_mfma_f32_16x16x32_bf16 v[30:33], v[172:175], v[204:207], v[30:33]
	v_mfma_f32_16x16x32_bf16 v[22:25], v[180:183], v[204:207], v[22:25]
	v_mfma_f32_16x16x32_bf16 v[14:17], v[172:175], v[212:215], v[14:17]
	v_mfma_f32_16x16x32_bf16 v[2:5], v[180:183], v[212:215], v[2:5]
	s_barrier
	s_add_i32 s88, s88, 2
	s_add_u32 s86, s86, 0x100
	s_addc_u32 s87, s87, 0
	s_cmp_gt_u32 s88, 13
	s_mov_b64 s[40:41], s[0:1]
	s_cbranch_scc0 .LBB0_988
	s_and_b64 vcc, exec, s[8:9]
	s_cbranch_vccz .LBB0_991
	s_barrier

.LBB0_1317:
	ds_read_b128 v[138:141], v132
	ds_read_b128 v[142:145], v132 offset:1024
	ds_read_b128 v[146:149], v132 offset:2048
	ds_read_b128 v[150:153], v132 offset:3072
	ds_read_b128 v[154:157], v133
	ds_read_b128 v[158:161], v133 offset:1024
	ds_read_b128 v[166:169], v133 offset:2048
	ds_read_b128 v[170:173], v133 offset:3072
	s_add_u32 s0, s46, 0xea3c0080
	s_addc_u32 s1, s47, -1
	s_cmp_lg_u32 s90, 12
	s_cselect_b32 s13, s0, 0
	s_cselect_b32 s12, s1, 0
	s_add_u32 s0, s8, s13
	s_addc_u32 s1, s9, s12
	s_add_u32 s34, s0, 0x80
	s_addc_u32 s35, s1, 0
	s_add_u32 s48, s4, s13
	s_addc_u32 s49, s5, s12
	ds_read_b128 v[174:177], v134
	ds_read_b128 v[184:187], v134 offset:1024
	ds_read_b128 v[188:191], v134 offset:2048
	ds_read_b128 v[192:195], v134 offset:3072
	ds_read_b128 v[196:199], v134 offset:4096
	ds_read_b128 v[200:203], v134 offset:5120
	ds_read_b128 v[204:207], v134 offset:6144
	ds_read_b128 v[208:211], v134 offset:7168
	s_add_u32 s12, s88, s46
	s_addc_u32 s13, s89, s47
	s_mov_b32 s91, m0
	s_mov_b32 m0, s87
	s_nop 4
	global_load_lds_dwordx4 v130, s[12:13]
	s_mov_b32 m0, s91
	s_add_u32 s12, s12, 0x20000
	s_addc_u32 s13, s13, 0
	s_add_i32 s91, s66, 0xe000
	s_mov_b32 s92, m0
	s_mov_b32 m0, s91
	s_nop 4
	global_load_lds_dwordx4 v130, s[12:13]
	s_mov_b32 m0, s92
	s_waitcnt vmcnt(8)
	s_waitcnt lgkmcnt(0)
	s_barrier
	v_mfma_f32_16x16x32_bf16 v[2:5], v[138:141], v[174:177], v[2:5]
	v_mfma_f32_16x16x32_bf16 v[6:9], v[146:149], v[174:177], v[6:9]
	v_mfma_f32_16x16x32_bf16 v[30:33], v[138:141], v[188:191], v[30:33]
	v_mfma_f32_16x16x32_bf16 v[34:37], v[146:149], v[188:191], v[34:37]
	v_mfma_f32_16x16x32_bf16 v[54:57], v[138:141], v[196:199], v[54:57]
	v_mfma_f32_16x16x32_bf16 v[50:53], v[146:149], v[196:199], v[50:53]
	v_mfma_f32_16x16x32_bf16 v[70:73], v[138:141], v[204:207], v[70:73]
	v_mfma_f32_16x16x32_bf16 v[66:69], v[146:149], v[204:207], v[66:69]
	v_mfma_f32_16x16x32_bf16 v[2:5], v[142:145], v[184:187], v[2:5]
	v_mfma_f32_16x16x32_bf16 v[6:9], v[150:153], v[184:187], v[6:9]
	v_mfma_f32_16x16x32_bf16 v[30:33], v[142:145], v[192:195], v[30:33]
	v_mfma_f32_16x16x32_bf16 v[34:37], v[150:153], v[192:195], v[34:37]
	v_mfma_f32_16x16x32_bf16 v[54:57], v[142:145], v[200:203], v[54:57]
	v_mfma_f32_16x16x32_bf16 v[50:53], v[150:153], v[200:203], v[50:53]
	v_mfma_f32_16x16x32_bf16 v[70:73], v[142:145], v[208:211], v[70:73]
	v_mfma_f32_16x16x32_bf16 v[66:69], v[150:153], v[208:211], v[66:69]
	v_mfma_f32_16x16x32_bf16 v[10:13], v[154:157], v[174:177], v[10:13]
	v_mfma_f32_16x16x32_bf16 v[14:17], v[166:169], v[174:177], v[14:17]
	v_mfma_f32_16x16x32_bf16 v[22:25], v[154:157], v[188:191], v[22:25]
	v_mfma_f32_16x16x32_bf16 v[18:21], v[166:169], v[188:191], v[18:21]
	v_mfma_f32_16x16x32_bf16 v[38:41], v[154:157], v[196:199], v[38:41]
	v_mfma_f32_16x16x32_bf16 v[26:29], v[166:169], v[196:199], v[26:29]
	v_mfma_f32_16x16x32_bf16 v[46:49], v[154:157], v[204:207], v[46:49]
	v_mfma_f32_16x16x32_bf16 v[42:45], v[166:169], v[204:207], v[42:45]
	v_mfma_f32_16x16x32_bf16 v[10:13], v[158:161], v[184:187], v[10:13]
	v_mfma_f32_16x16x32_bf16 v[14:17], v[170:173], v[184:187], v[14:17]
	v_mfma_f32_16x16x32_bf16 v[22:25], v[158:161], v[192:195], v[22:25]
	v_mfma_f32_16x16x32_bf16 v[18:21], v[170:173], v[192:195], v[18:21]
	v_mfma_f32_16x16x32_bf16 v[38:41], v[158:161], v[200:203], v[38:41]
	v_mfma_f32_16x16x32_bf16 v[26:29], v[170:173], v[200:203], v[26:29]
	v_mfma_f32_16x16x32_bf16 v[46:49], v[158:161], v[208:211], v[46:49]
	v_mfma_f32_16x16x32_bf16 v[42:45], v[170:173], v[208:211], v[42:45]
	s_barrier
	ds_read_b128 v[174:177], v134 offset:16384
	ds_read_b128 v[184:187], v134 offset:17408
	ds_read_b128 v[188:191], v134 offset:18432
	ds_read_b128 v[192:195], v134 offset:19456
	ds_read_b128 v[196:199], v134 offset:20480
	ds_read_b128 v[200:203], v134 offset:21504
	ds_read_b128 v[204:207], v134 offset:22528
	ds_read_b128 v[208:211], v134 offset:23552
	s_mov_b32 s12, m0
	s_mov_b32 m0, s67
	s_nop 4
	global_load_lds_dwordx4 v131, s[48:49]
	s_mov_b32 m0, s12
	s_add_u32 s12, s48, 0x20000
	s_addc_u32 s13, s49, 0
	s_mov_b32 s91, m0
	s_mov_b32 m0, s73
	s_nop 4
	global_load_lds_dwordx4 v131, s[12:13]
	s_mov_b32 m0, s91
	s_add_u32 s12, s48, 0x40000
	s_addc_u32 s13, s49, 0
	s_mov_b32 s91, m0
	s_mov_b32 m0, s74
	s_nop 4
	global_load_lds_dwordx4 v131, s[12:13]
	s_mov_b32 m0, s91
	s_add_u32 s12, s48, 0x60000
	s_addc_u32 s13, s49, 0
	s_mov_b32 s91, m0
	s_mov_b32 m0, s75
	s_nop 4
	global_load_lds_dwordx4 v131, s[12:13]
	s_mov_b32 m0, s91
	s_mov_b32 s12, m0
	s_mov_b32 m0, s66
	s_nop 4
	global_load_lds_dwordx4 v130, s[0:1]
	s_mov_b32 m0, s12
	s_add_u32 s12, s0, 0x20000
	s_addc_u32 s13, s1, 0
	s_mov_b32 s91, m0
	s_mov_b32 m0, s76
	s_nop 4
	global_load_lds_dwordx4 v130, s[12:13]
	s_mov_b32 m0, s91
	s_waitcnt vmcnt(8)
	s_waitcnt lgkmcnt(0)
	s_barrier
	v_mfma_f32_16x16x32_bf16 v[82:85], v[138:141], v[174:177], v[82:85]
	v_mfma_f32_16x16x32_bf16 v[74:77], v[146:149], v[174:177], v[74:77]
	v_mfma_f32_16x16x32_bf16 v[98:101], v[138:141], v[188:191], v[98:101]
	v_mfma_f32_16x16x32_bf16 v[90:93], v[146:149], v[188:191], v[90:93]
	v_mfma_f32_16x16x32_bf16 v[118:121], v[138:141], v[196:199], v[118:121]
	v_mfma_f32_16x16x32_bf16 v[114:117], v[146:149], v[196:199], v[114:117]
	v_mfma_f32_16x16x32_bf16 v[126:129], v[138:141], v[204:207], v[126:129]
	v_mfma_f32_16x16x32_bf16 v[122:125], v[146:149], v[204:207], v[122:125]
	v_mfma_f32_16x16x32_bf16 v[82:85], v[142:145], v[184:187], v[82:85]
	v_mfma_f32_16x16x32_bf16 v[74:77], v[150:153], v[184:187], v[74:77]
	v_mfma_f32_16x16x32_bf16 v[98:101], v[142:145], v[192:195], v[98:101]
	v_mfma_f32_16x16x32_bf16 v[90:93], v[150:153], v[192:195], v[90:93]
	v_mfma_f32_16x16x32_bf16 v[118:121], v[142:145], v[200:203], v[118:121]
	v_mfma_f32_16x16x32_bf16 v[114:117], v[150:153], v[200:203], v[114:117]
	v_mfma_f32_16x16x32_bf16 v[126:129], v[142:145], v[208:211], v[126:129]
	v_mfma_f32_16x16x32_bf16 v[122:125], v[150:153], v[208:211], v[122:125]
	v_mfma_f32_16x16x32_bf16 v[62:65], v[154:157], v[174:177], v[62:65]
	v_mfma_f32_16x16x32_bf16 v[58:61], v[166:169], v[174:177], v[58:61]
	v_mfma_f32_16x16x32_bf16 v[86:89], v[154:157], v[188:191], v[86:89]
	v_mfma_f32_16x16x32_bf16 v[78:81], v[166:169], v[188:191], v[78:81]
	v_mfma_f32_16x16x32_bf16 v[102:105], v[154:157], v[196:199], v[102:105]
	v_mfma_f32_16x16x32_bf16 v[94:97], v[166:169], v[196:199], v[94:97]
	v_mfma_f32_16x16x32_bf16 v[110:113], v[154:157], v[204:207], v[110:113]
	v_mfma_f32_16x16x32_bf16 v[106:109], v[166:169], v[204:207], v[106:109]
	v_mfma_f32_16x16x32_bf16 v[62:65], v[158:161], v[184:187], v[62:65]
	v_mfma_f32_16x16x32_bf16 v[58:61], v[170:173], v[184:187], v[58:61]
	v_mfma_f32_16x16x32_bf16 v[86:89], v[158:161], v[192:195], v[86:89]
	v_mfma_f32_16x16x32_bf16 v[78:81], v[170:173], v[192:195], v[78:81]
	v_mfma_f32_16x16x32_bf16 v[102:105], v[158:161], v[200:203], v[102:105]
	v_mfma_f32_16x16x32_bf16 v[94:97], v[170:173], v[200:203], v[94:97]
	v_mfma_f32_16x16x32_bf16 v[110:113], v[158:161], v[208:211], v[110:113]
	v_mfma_f32_16x16x32_bf16 v[106:109], v[170:173], v[208:211], v[106:109]
	s_barrier
	ds_read_b128 v[138:141], v135
	ds_read_b128 v[142:145], v135 offset:1024
	ds_read_b128 v[146:149], v135 offset:2048
	ds_read_b128 v[150:153], v135 offset:3072
	ds_read_b128 v[154:157], v136
	ds_read_b128 v[158:161], v136 offset:1024
	ds_read_b128 v[166:169], v136 offset:2048
	ds_read_b128 v[170:173], v136 offset:3072
	ds_read_b128 v[174:177], v134 offset:32768
	ds_read_b128 v[184:187], v134 offset:33792
	ds_read_b128 v[188:191], v134 offset:34816
	ds_read_b128 v[192:195], v134 offset:35840
	ds_read_b128 v[196:199], v134 offset:36864
	ds_read_b128 v[200:203], v134 offset:37888
	ds_read_b128 v[204:207], v134 offset:38912
	ds_read_b128 v[208:211], v134 offset:39936
	s_add_u32 s12, s0, 0x40000
	s_addc_u32 s13, s1, 0
	s_mov_b32 s91, m0
	s_mov_b32 m0, s77
	s_nop 4
	global_load_lds_dwordx4 v130, s[12:13]
	s_mov_b32 m0, s91
	s_add_u32 s12, s0, 0x60000
	s_addc_u32 s13, s1, 0
	s_mov_b32 s91, m0
	s_mov_b32 m0, s79
	s_nop 4
	global_load_lds_dwordx4 v130, s[12:13]
	s_mov_b32 m0, s91
	s_waitcnt vmcnt(8)
	s_waitcnt lgkmcnt(0)
	s_barrier
	v_mfma_f32_16x16x32_bf16 v[2:5], v[138:141], v[174:177], v[2:5]
	v_mfma_f32_16x16x32_bf16 v[6:9], v[146:149], v[174:177], v[6:9]
	v_mfma_f32_16x16x32_bf16 v[30:33], v[138:141], v[188:191], v[30:33]
	v_mfma_f32_16x16x32_bf16 v[34:37], v[146:149], v[188:191], v[34:37]
	v_mfma_f32_16x16x32_bf16 v[54:57], v[138:141], v[196:199], v[54:57]
	v_mfma_f32_16x16x32_bf16 v[50:53], v[146:149], v[196:199], v[50:53]
	v_mfma_f32_16x16x32_bf16 v[70:73], v[138:141], v[204:207], v[70:73]
	v_mfma_f32_16x16x32_bf16 v[66:69], v[146:149], v[204:207], v[66:69]
	v_mfma_f32_16x16x32_bf16 v[2:5], v[142:145], v[184:187], v[2:5]
	v_mfma_f32_16x16x32_bf16 v[6:9], v[150:153], v[184:187], v[6:9]
	v_mfma_f32_16x16x32_bf16 v[30:33], v[142:145], v[192:195], v[30:33]
	v_mfma_f32_16x16x32_bf16 v[34:37], v[150:153], v[192:195], v[34:37]
	v_mfma_f32_16x16x32_bf16 v[54:57], v[142:145], v[200:203], v[54:57]
	v_mfma_f32_16x16x32_bf16 v[50:53], v[150:153], v[200:203], v[50:53]
	v_mfma_f32_16x16x32_bf16 v[70:73], v[142:145], v[208:211], v[70:73]
	v_mfma_f32_16x16x32_bf16 v[66:69], v[150:153], v[208:211], v[66:69]
	v_mfma_f32_16x16x32_bf16 v[10:13], v[154:157], v[174:177], v[10:13]
	v_mfma_f32_16x16x32_bf16 v[14:17], v[166:169], v[174:177], v[14:17]
	v_mfma_f32_16x16x32_bf16 v[22:25], v[154:157], v[188:191], v[22:25]
	v_mfma_f32_16x16x32_bf16 v[18:21], v[166:169], v[188:191], v[18:21]
	v_mfma_f32_16x16x32_bf16 v[38:41], v[154:157], v[196:199], v[38:41]
	v_mfma_f32_16x16x32_bf16 v[26:29], v[166:169], v[196:199], v[26:29]
	v_mfma_f32_16x16x32_bf16 v[46:49], v[154:157], v[204:207], v[46:49]
	v_mfma_f32_16x16x32_bf16 v[42:45], v[166:169], v[204:207], v[42:45]
	v_mfma_f32_16x16x32_bf16 v[10:13], v[158:161], v[184:187], v[10:13]
	v_mfma_f32_16x16x32_bf16 v[14:17], v[170:173], v[184:187], v[14:17]
	v_mfma_f32_16x16x32_bf16 v[22:25], v[158:161], v[192:195], v[22:25]
	v_mfma_f32_16x16x32_bf16 v[18:21], v[170:173], v[192:195], v[18:21]
	v_mfma_f32_16x16x32_bf16 v[38:41], v[158:161], v[200:203], v[38:41]
	v_mfma_f32_16x16x32_bf16 v[26:29], v[170:173], v[200:203], v[26:29]
	v_mfma_f32_16x16x32_bf16 v[46:49], v[158:161], v[208:211], v[46:49]
	v_mfma_f32_16x16x32_bf16 v[42:45], v[170:173], v[208:211], v[42:45]
	s_barrier
	s_add_u32 s12, s48, 0x80
	s_addc_u32 s13, s49, 0
	ds_read_b128 v[174:177], v134 offset:49152
	ds_read_b128 v[184:187], v134 offset:50176
	ds_read_b128 v[188:191], v134 offset:51200
	ds_read_b128 v[192:195], v134 offset:52224
	ds_read_b128 v[196:199], v134 offset:53248
	ds_read_b128 v[200:203], v134 offset:54272
	ds_read_b128 v[204:207], v134 offset:55296
	ds_read_b128 v[208:211], v134 offset:56320
	s_mov_b32 s91, m0
	s_mov_b32 m0, s80
	s_nop 4
	global_load_lds_dwordx4 v131, s[12:13]
	s_mov_b32 m0, s91
	s_add_u32 s12, s48, 0x20080
	s_addc_u32 s13, s49, 0
	s_mov_b32 s91, m0
	s_mov_b32 m0, s81
	s_nop 4
	global_load_lds_dwordx4 v131, s[12:13]
	s_mov_b32 m0, s91
	s_add_u32 s12, s48, 0x40080
	s_addc_u32 s13, s49, 0
	s_mov_b32 s91, m0
	s_mov_b32 m0, s85
	s_nop 4
	global_load_lds_dwordx4 v131, s[12:13]
	s_mov_b32 m0, s91
	s_add_u32 s12, s48, 0x60080
	s_addc_u32 s13, s49, 0
	s_mov_b32 s48, m0
	s_mov_b32 m0, s86
	s_nop 4
	global_load_lds_dwordx4 v131, s[12:13]
	s_mov_b32 m0, s48
	s_mov_b32 s12, m0
	s_mov_b32 m0, s82
	s_nop 4
	global_load_lds_dwordx4 v130, s[34:35]
	s_mov_b32 m0, s12
	s_add_u32 s0, s0, 0x20080
	s_addc_u32 s1, s1, 0
	s_mov_b32 s12, m0
	s_mov_b32 m0, s84
	s_nop 4
	global_load_lds_dwordx4 v130, s[0:1]
	s_mov_b32 m0, s12
	s_waitcnt vmcnt(8)
	s_waitcnt lgkmcnt(0)
	s_barrier
	v_mfma_f32_16x16x32_bf16 v[82:85], v[138:141], v[174:177], v[82:85]
	v_mfma_f32_16x16x32_bf16 v[74:77], v[146:149], v[174:177], v[74:77]
	v_mfma_f32_16x16x32_bf16 v[98:101], v[138:141], v[188:191], v[98:101]
	v_mfma_f32_16x16x32_bf16 v[90:93], v[146:149], v[188:191], v[90:93]
	v_mfma_f32_16x16x32_bf16 v[118:121], v[138:141], v[196:199], v[118:121]
	v_mfma_f32_16x16x32_bf16 v[114:117], v[146:149], v[196:199], v[114:117]
	v_mfma_f32_16x16x32_bf16 v[126:129], v[138:141], v[204:207], v[126:129]
	v_mfma_f32_16x16x32_bf16 v[122:125], v[146:149], v[204:207], v[122:125]
	v_mfma_f32_16x16x32_bf16 v[82:85], v[142:145], v[184:187], v[82:85]
	v_mfma_f32_16x16x32_bf16 v[74:77], v[150:153], v[184:187], v[74:77]
	v_mfma_f32_16x16x32_bf16 v[98:101], v[142:145], v[192:195], v[98:101]
	v_mfma_f32_16x16x32_bf16 v[90:93], v[150:153], v[192:195], v[90:93]
	v_mfma_f32_16x16x32_bf16 v[118:121], v[142:145], v[200:203], v[118:121]
	v_mfma_f32_16x16x32_bf16 v[114:117], v[150:153], v[200:203], v[114:117]
	v_mfma_f32_16x16x32_bf16 v[126:129], v[142:145], v[208:211], v[126:129]
	v_mfma_f32_16x16x32_bf16 v[122:125], v[150:153], v[208:211], v[122:125]
	v_mfma_f32_16x16x32_bf16 v[62:65], v[154:157], v[174:177], v[62:65]
	v_mfma_f32_16x16x32_bf16 v[58:61], v[166:169], v[174:177], v[58:61]
	v_mfma_f32_16x16x32_bf16 v[86:89], v[154:157], v[188:191], v[86:89]
	v_mfma_f32_16x16x32_bf16 v[78:81], v[166:169], v[188:191], v[78:81]
	v_mfma_f32_16x16x32_bf16 v[102:105], v[154:157], v[196:199], v[102:105]
	v_mfma_f32_16x16x32_bf16 v[94:97], v[166:169], v[196:199], v[94:97]
	v_mfma_f32_16x16x32_bf16 v[110:113], v[154:157], v[204:207], v[110:113]
	v_mfma_f32_16x16x32_bf16 v[106:109], v[166:169], v[204:207], v[106:109]
	v_mfma_f32_16x16x32_bf16 v[62:65], v[158:161], v[184:187], v[62:65]
	v_mfma_f32_16x16x32_bf16 v[58:61], v[170:173], v[184:187], v[58:61]
	v_mfma_f32_16x16x32_bf16 v[86:89], v[158:161], v[192:195], v[86:89]
	v_mfma_f32_16x16x32_bf16 v[78:81], v[170:173], v[192:195], v[78:81]
	v_mfma_f32_16x16x32_bf16 v[102:105], v[158:161], v[200:203], v[102:105]
	v_mfma_f32_16x16x32_bf16 v[94:97], v[170:173], v[200:203], v[94:97]
	v_mfma_f32_16x16x32_bf16 v[110:113], v[158:161], v[208:211], v[110:113]
	v_mfma_f32_16x16x32_bf16 v[106:109], v[170:173], v[208:211], v[106:109]
	s_barrier
	s_add_i32 s90, s90, 2
	s_add_u32 s46, s46, 0x100
	s_addc_u32 s47, s47, 0
	s_cmp_lt_u32 s90, 14
	s_cbranch_scc1 .LBB0_1317
	s_waitcnt vmcnt(0)
	s_cmpk_gt_u32 s65, 0xff
	s_cbranch_scc1 .LBB0_1320
	s_barrier

.LBB0_1424:
	v_add_u32_e32 v134, 0x10000, v139
	ds_read_b128 v[142:145], v134
	ds_read_b128 v[146:149], v134 offset:1024
	ds_read_b128 v[150:153], v134 offset:2048
	ds_read_b128 v[154:157], v134 offset:3072
	v_add_u32_e32 v134, 0x14000, v139
	ds_read_b128 v[158:161], v134
	ds_read_b128 v[162:165], v134 offset:1024
	ds_read_b128 v[166:169], v134 offset:2048
	ds_read_b128 v[170:173], v134 offset:3072
	s_add_u32 s0, s36, 0x100
	s_addc_u32 s1, s37, 0
	s_cmp_eq_u32 s66, 12
	s_cselect_b32 s34, s15, s0
	s_cselect_b32 s35, s14, s1
	s_cselect_b32 s40, s21, s64
	s_cselect_b32 s41, s11, s65
	s_add_u32 s38, s34, 0x80
	s_addc_u32 s39, s35, 0
	ds_read_b128 v[174:177], v140
	ds_read_b128 v[178:181], v140 offset:1024
	ds_read_b128 v[182:185], v140 offset:2048
	ds_read_b128 v[186:189], v140 offset:3072
	ds_read_b128 v[190:193], v140 offset:4096
	ds_read_b128 v[194:197], v140 offset:5120
	ds_read_b128 v[198:201], v140 offset:6144
	ds_read_b128 v[202:205], v140 offset:7168
	s_add_u32 s12, s36, 0x40080
	s_addc_u32 s13, s37, 0
	s_mov_b32 s67, m0
	s_mov_b32 m0, s59
	s_nop 4
	global_load_lds_dwordx4 v1, s[12:13]
	s_mov_b32 m0, s67
	s_add_u32 s12, s36, 0x60080
	s_addc_u32 s13, s37, 0
	s_add_i32 s36, s27, 0xe000
	s_mov_b32 s37, m0
	s_mov_b32 m0, s36
	s_nop 4
	global_load_lds_dwordx4 v1, s[12:13]
	s_mov_b32 m0, s37
	s_waitcnt vmcnt(8)
	s_waitcnt lgkmcnt(0)
	s_barrier
	v_mfma_f32_16x16x32_bf16 v[122:125], v[142:145], v[174:177], v[122:125]
	v_mfma_f32_16x16x32_bf16 v[114:117], v[150:153], v[174:177], v[114:117]
	v_mfma_f32_16x16x32_bf16 v[106:109], v[142:145], v[182:185], v[106:109]
	v_mfma_f32_16x16x32_bf16 v[98:101], v[150:153], v[182:185], v[98:101]
	v_mfma_f32_16x16x32_bf16 v[90:93], v[142:145], v[190:193], v[90:93]
	v_mfma_f32_16x16x32_bf16 v[82:85], v[150:153], v[190:193], v[82:85]
	v_mfma_f32_16x16x32_bf16 v[74:77], v[142:145], v[198:201], v[74:77]
	v_mfma_f32_16x16x32_bf16 v[66:69], v[150:153], v[198:201], v[66:69]
	v_mfma_f32_16x16x32_bf16 v[122:125], v[146:149], v[178:181], v[122:125]
	v_mfma_f32_16x16x32_bf16 v[114:117], v[154:157], v[178:181], v[114:117]
	v_mfma_f32_16x16x32_bf16 v[106:109], v[146:149], v[186:189], v[106:109]
	v_mfma_f32_16x16x32_bf16 v[98:101], v[154:157], v[186:189], v[98:101]
	v_mfma_f32_16x16x32_bf16 v[90:93], v[146:149], v[194:197], v[90:93]
	v_mfma_f32_16x16x32_bf16 v[82:85], v[154:157], v[194:197], v[82:85]
	v_mfma_f32_16x16x32_bf16 v[74:77], v[146:149], v[202:205], v[74:77]
	v_mfma_f32_16x16x32_bf16 v[66:69], v[154:157], v[202:205], v[66:69]
	v_mfma_f32_16x16x32_bf16 v[126:129], v[158:161], v[174:177], v[126:129]
	v_mfma_f32_16x16x32_bf16 v[118:121], v[166:169], v[174:177], v[118:121]
	v_mfma_f32_16x16x32_bf16 v[110:113], v[158:161], v[182:185], v[110:113]
	v_mfma_f32_16x16x32_bf16 v[102:105], v[166:169], v[182:185], v[102:105]
	v_mfma_f32_16x16x32_bf16 v[94:97], v[158:161], v[190:193], v[94:97]
	v_mfma_f32_16x16x32_bf16 v[86:89], v[166:169], v[190:193], v[86:89]
	v_mfma_f32_16x16x32_bf16 v[78:81], v[158:161], v[198:201], v[78:81]
	v_mfma_f32_16x16x32_bf16 v[70:73], v[166:169], v[198:201], v[70:73]
	v_mfma_f32_16x16x32_bf16 v[126:129], v[162:165], v[178:181], v[126:129]
	v_mfma_f32_16x16x32_bf16 v[118:121], v[170:173], v[178:181], v[118:121]
	v_mfma_f32_16x16x32_bf16 v[110:113], v[162:165], v[186:189], v[110:113]
	v_mfma_f32_16x16x32_bf16 v[102:105], v[170:173], v[186:189], v[102:105]
	v_mfma_f32_16x16x32_bf16 v[94:97], v[162:165], v[194:197], v[94:97]
	v_mfma_f32_16x16x32_bf16 v[86:89], v[170:173], v[194:197], v[86:89]
	v_mfma_f32_16x16x32_bf16 v[78:81], v[162:165], v[202:205], v[78:81]
	v_mfma_f32_16x16x32_bf16 v[70:73], v[170:173], v[202:205], v[70:73]
	s_barrier
	ds_read_b128 v[174:177], v140 offset:16384
	ds_read_b128 v[178:181], v140 offset:17408
	ds_read_b128 v[182:185], v140 offset:18432
	ds_read_b128 v[186:189], v140 offset:19456
	ds_read_b128 v[190:193], v140 offset:20480
	ds_read_b128 v[194:197], v140 offset:21504
	ds_read_b128 v[198:201], v140 offset:22528
	ds_read_b128 v[202:205], v140 offset:23552
	s_mov_b32 s12, m0
	s_mov_b32 m0, s46
	s_nop 4
	global_load_lds_dwordx4 v136, s[40:41]
	s_mov_b32 m0, s12
	s_add_u32 s12, s40, 0x20000
	s_addc_u32 s13, s41, 0
	s_mov_b32 s36, m0
	s_mov_b32 m0, s47
	s_nop 4
	global_load_lds_dwordx4 v136, s[12:13]
	s_mov_b32 m0, s36
	s_add_u32 s12, s40, 0x40000
	s_addc_u32 s13, s41, 0
	s_mov_b32 s36, m0
	s_mov_b32 m0, s48
	s_nop 4
	global_load_lds_dwordx4 v136, s[12:13]
	s_mov_b32 m0, s36
	s_add_u32 s12, s40, 0x60000
	s_addc_u32 s13, s41, 0
	s_mov_b32 s36, m0
	s_mov_b32 m0, s49
	s_nop 4
	global_load_lds_dwordx4 v136, s[12:13]
	s_mov_b32 m0, s36
	s_mov_b32 s12, m0
	s_mov_b32 m0, s27
	s_nop 4
	global_load_lds_dwordx4 v1, s[34:35]
	s_mov_b32 m0, s12
	s_add_u32 s12, s34, 0x20000
	s_addc_u32 s13, s35, 0
	s_mov_b32 s36, m0
	s_mov_b32 m0, s50
	s_nop 4
	global_load_lds_dwordx4 v1, s[12:13]
	s_mov_b32 m0, s36
	s_waitcnt vmcnt(8)
	s_waitcnt lgkmcnt(0)
	s_barrier
	v_mfma_f32_16x16x32_bf16 v[58:61], v[142:145], v[174:177], v[58:61]
	v_mfma_f32_16x16x32_bf16 v[50:53], v[150:153], v[174:177], v[50:53]
	v_mfma_f32_16x16x32_bf16 v[42:45], v[142:145], v[182:185], v[42:45]
	v_mfma_f32_16x16x32_bf16 v[34:37], v[150:153], v[182:185], v[34:37]
	v_mfma_f32_16x16x32_bf16 v[26:29], v[142:145], v[190:193], v[26:29]
	v_mfma_f32_16x16x32_bf16 v[18:21], v[150:153], v[190:193], v[18:21]
	v_mfma_f32_16x16x32_bf16 v[10:13], v[142:145], v[198:201], v[10:13]
	v_mfma_f32_16x16x32_bf16 v[6:9], v[150:153], v[198:201], v[6:9]
	v_mfma_f32_16x16x32_bf16 v[58:61], v[146:149], v[178:181], v[58:61]
	v_mfma_f32_16x16x32_bf16 v[50:53], v[154:157], v[178:181], v[50:53]
	v_mfma_f32_16x16x32_bf16 v[42:45], v[146:149], v[186:189], v[42:45]
	v_mfma_f32_16x16x32_bf16 v[34:37], v[154:157], v[186:189], v[34:37]
	v_mfma_f32_16x16x32_bf16 v[26:29], v[146:149], v[194:197], v[26:29]
	v_mfma_f32_16x16x32_bf16 v[18:21], v[154:157], v[194:197], v[18:21]
	v_mfma_f32_16x16x32_bf16 v[10:13], v[146:149], v[202:205], v[10:13]
	v_mfma_f32_16x16x32_bf16 v[6:9], v[154:157], v[202:205], v[6:9]
	v_mfma_f32_16x16x32_bf16 v[62:65], v[158:161], v[174:177], v[62:65]
	v_mfma_f32_16x16x32_bf16 v[54:57], v[166:169], v[174:177], v[54:57]
	v_mfma_f32_16x16x32_bf16 v[46:49], v[158:161], v[182:185], v[46:49]
	v_mfma_f32_16x16x32_bf16 v[38:41], v[166:169], v[182:185], v[38:41]
	v_mfma_f32_16x16x32_bf16 v[30:33], v[158:161], v[190:193], v[30:33]
	v_mfma_f32_16x16x32_bf16 v[22:25], v[166:169], v[190:193], v[22:25]
	v_mfma_f32_16x16x32_bf16 v[14:17], v[158:161], v[198:201], v[14:17]
	v_mfma_f32_16x16x32_bf16 v[2:5], v[166:169], v[198:201], v[2:5]
	v_mfma_f32_16x16x32_bf16 v[62:65], v[162:165], v[178:181], v[62:65]
	v_mfma_f32_16x16x32_bf16 v[54:57], v[170:173], v[178:181], v[54:57]
	v_mfma_f32_16x16x32_bf16 v[46:49], v[162:165], v[186:189], v[46:49]
	v_mfma_f32_16x16x32_bf16 v[38:41], v[170:173], v[186:189], v[38:41]
	v_mfma_f32_16x16x32_bf16 v[30:33], v[162:165], v[194:197], v[30:33]
	v_mfma_f32_16x16x32_bf16 v[22:25], v[170:173], v[194:197], v[22:25]
	v_mfma_f32_16x16x32_bf16 v[14:17], v[162:165], v[202:205], v[14:17]
	v_mfma_f32_16x16x32_bf16 v[2:5], v[170:173], v[202:205], v[2:5]
	s_barrier
	v_add_u32_e32 v134, 0x18000, v139
	ds_read_b128 v[142:145], v134
	ds_read_b128 v[146:149], v134 offset:1024
	ds_read_b128 v[150:153], v134 offset:2048
	ds_read_b128 v[154:157], v134 offset:3072
	v_add_u32_e32 v134, 0x1c000, v139
	ds_read_b128 v[158:161], v134
	ds_read_b128 v[162:165], v134 offset:1024
	ds_read_b128 v[166:169], v134 offset:2048
	ds_read_b128 v[170:173], v134 offset:3072
	ds_read_b128 v[174:177], v140 offset:32768
	ds_read_b128 v[178:181], v140 offset:33792
	ds_read_b128 v[182:185], v140 offset:34816
	ds_read_b128 v[186:189], v140 offset:35840
	ds_read_b128 v[190:193], v140 offset:36864
	ds_read_b128 v[194:197], v140 offset:37888
	ds_read_b128 v[198:201], v140 offset:38912
	ds_read_b128 v[202:205], v140 offset:39936
	s_add_u32 s12, s34, 0x40000
	s_addc_u32 s13, s35, 0
	s_mov_b32 s36, m0
	s_mov_b32 m0, s51
	s_nop 4
	global_load_lds_dwordx4 v1, s[12:13]
	s_mov_b32 m0, s36
	s_add_u32 s12, s34, 0x60000
	s_addc_u32 s13, s35, 0
	s_mov_b32 s36, m0
	s_mov_b32 m0, s52
	s_nop 4
	global_load_lds_dwordx4 v1, s[12:13]
	s_mov_b32 m0, s36
	s_waitcnt vmcnt(8)
	s_waitcnt lgkmcnt(0)
	s_barrier
	v_mfma_f32_16x16x32_bf16 v[122:125], v[142:145], v[174:177], v[122:125]
	v_mfma_f32_16x16x32_bf16 v[114:117], v[150:153], v[174:177], v[114:117]
	v_mfma_f32_16x16x32_bf16 v[106:109], v[142:145], v[182:185], v[106:109]
	v_mfma_f32_16x16x32_bf16 v[98:101], v[150:153], v[182:185], v[98:101]
	v_mfma_f32_16x16x32_bf16 v[90:93], v[142:145], v[190:193], v[90:93]
	v_mfma_f32_16x16x32_bf16 v[82:85], v[150:153], v[190:193], v[82:85]
	v_mfma_f32_16x16x32_bf16 v[74:77], v[142:145], v[198:201], v[74:77]
	v_mfma_f32_16x16x32_bf16 v[66:69], v[150:153], v[198:201], v[66:69]
	v_mfma_f32_16x16x32_bf16 v[122:125], v[146:149], v[178:181], v[122:125]
	v_mfma_f32_16x16x32_bf16 v[114:117], v[154:157], v[178:181], v[114:117]
	v_mfma_f32_16x16x32_bf16 v[106:109], v[146:149], v[186:189], v[106:109]
	v_mfma_f32_16x16x32_bf16 v[98:101], v[154:157], v[186:189], v[98:101]
	v_mfma_f32_16x16x32_bf16 v[90:93], v[146:149], v[194:197], v[90:93]
	v_mfma_f32_16x16x32_bf16 v[82:85], v[154:157], v[194:197], v[82:85]
	v_mfma_f32_16x16x32_bf16 v[74:77], v[146:149], v[202:205], v[74:77]
	v_mfma_f32_16x16x32_bf16 v[66:69], v[154:157], v[202:205], v[66:69]
	v_mfma_f32_16x16x32_bf16 v[126:129], v[158:161], v[174:177], v[126:129]
	v_mfma_f32_16x16x32_bf16 v[118:121], v[166:169], v[174:177], v[118:121]
	v_mfma_f32_16x16x32_bf16 v[110:113], v[158:161], v[182:185], v[110:113]
	v_mfma_f32_16x16x32_bf16 v[102:105], v[166:169], v[182:185], v[102:105]
	v_mfma_f32_16x16x32_bf16 v[94:97], v[158:161], v[190:193], v[94:97]
	v_mfma_f32_16x16x32_bf16 v[86:89], v[166:169], v[190:193], v[86:89]
	v_mfma_f32_16x16x32_bf16 v[78:81], v[158:161], v[198:201], v[78:81]
	v_mfma_f32_16x16x32_bf16 v[70:73], v[166:169], v[198:201], v[70:73]
	v_mfma_f32_16x16x32_bf16 v[126:129], v[162:165], v[178:181], v[126:129]
	v_mfma_f32_16x16x32_bf16 v[118:121], v[170:173], v[178:181], v[118:121]
	v_mfma_f32_16x16x32_bf16 v[110:113], v[162:165], v[186:189], v[110:113]
	v_mfma_f32_16x16x32_bf16 v[102:105], v[170:173], v[186:189], v[102:105]
	v_mfma_f32_16x16x32_bf16 v[94:97], v[162:165], v[194:197], v[94:97]
	v_mfma_f32_16x16x32_bf16 v[86:89], v[170:173], v[194:197], v[86:89]
	v_mfma_f32_16x16x32_bf16 v[78:81], v[162:165], v[202:205], v[78:81]
	v_mfma_f32_16x16x32_bf16 v[70:73], v[170:173], v[202:205], v[70:73]
	s_barrier
	s_add_u32 s12, s40, 0x80
	s_addc_u32 s13, s41, 0
	ds_read_b128 v[174:177], v140 offset:49152
	ds_read_b128 v[178:181], v140 offset:50176
	ds_read_b128 v[182:185], v140 offset:51200
	ds_read_b128 v[186:189], v140 offset:52224
	ds_read_b128 v[190:193], v140 offset:53248
	ds_read_b128 v[194:197], v140 offset:54272
	ds_read_b128 v[198:201], v140 offset:55296
	ds_read_b128 v[202:205], v140 offset:56320
	s_mov_b32 s36, m0
	s_mov_b32 m0, s53
	s_nop 4
	global_load_lds_dwordx4 v136, s[12:13]
	s_mov_b32 m0, s36
	s_add_u32 s12, s40, 0x20080
	s_addc_u32 s13, s41, 0
	s_mov_b32 s36, m0
	s_mov_b32 m0, s54
	s_nop 4
	global_load_lds_dwordx4 v136, s[12:13]
	s_mov_b32 m0, s36
	s_add_u32 s12, s40, 0x40080
	s_addc_u32 s13, s41, 0
	s_mov_b32 s36, m0
	s_mov_b32 m0, s57
	s_nop 4
	global_load_lds_dwordx4 v136, s[12:13]
	s_mov_b32 m0, s36
	s_add_u32 s12, s40, 0x60080
	s_addc_u32 s13, s41, 0
	s_mov_b32 s36, m0
	s_mov_b32 m0, s58
	s_nop 4
	global_load_lds_dwordx4 v136, s[12:13]
	s_mov_b32 m0, s36
	s_mov_b32 s12, m0
	s_mov_b32 m0, s55
	s_nop 4
	global_load_lds_dwordx4 v1, s[38:39]
	s_mov_b32 m0, s12
	s_add_u32 s12, s34, 0x20080
	s_addc_u32 s13, s35, 0
	s_mov_b32 s34, m0
	s_mov_b32 m0, s56
	s_nop 4
	global_load_lds_dwordx4 v1, s[12:13]
	s_mov_b32 m0, s34
	s_waitcnt vmcnt(8)
	s_waitcnt lgkmcnt(0)
	s_barrier
	v_mfma_f32_16x16x32_bf16 v[58:61], v[142:145], v[174:177], v[58:61]
	v_mfma_f32_16x16x32_bf16 v[50:53], v[150:153], v[174:177], v[50:53]
	v_mfma_f32_16x16x32_bf16 v[42:45], v[142:145], v[182:185], v[42:45]
	v_mfma_f32_16x16x32_bf16 v[34:37], v[150:153], v[182:185], v[34:37]
	v_mfma_f32_16x16x32_bf16 v[26:29], v[142:145], v[190:193], v[26:29]
	v_mfma_f32_16x16x32_bf16 v[18:21], v[150:153], v[190:193], v[18:21]
	v_mfma_f32_16x16x32_bf16 v[10:13], v[142:145], v[198:201], v[10:13]
	v_mfma_f32_16x16x32_bf16 v[6:9], v[150:153], v[198:201], v[6:9]
	v_mfma_f32_16x16x32_bf16 v[58:61], v[146:149], v[178:181], v[58:61]
	v_mfma_f32_16x16x32_bf16 v[50:53], v[154:157], v[178:181], v[50:53]
	v_mfma_f32_16x16x32_bf16 v[42:45], v[146:149], v[186:189], v[42:45]
	v_mfma_f32_16x16x32_bf16 v[34:37], v[154:157], v[186:189], v[34:37]
	v_mfma_f32_16x16x32_bf16 v[26:29], v[146:149], v[194:197], v[26:29]
	v_mfma_f32_16x16x32_bf16 v[18:21], v[154:157], v[194:197], v[18:21]
	v_mfma_f32_16x16x32_bf16 v[10:13], v[146:149], v[202:205], v[10:13]
	v_mfma_f32_16x16x32_bf16 v[6:9], v[154:157], v[202:205], v[6:9]
	v_mfma_f32_16x16x32_bf16 v[62:65], v[158:161], v[174:177], v[62:65]
	v_mfma_f32_16x16x32_bf16 v[54:57], v[166:169], v[174:177], v[54:57]
	v_mfma_f32_16x16x32_bf16 v[46:49], v[158:161], v[182:185], v[46:49]
	v_mfma_f32_16x16x32_bf16 v[38:41], v[166:169], v[182:185], v[38:41]
	v_mfma_f32_16x16x32_bf16 v[30:33], v[158:161], v[190:193], v[30:33]
	v_mfma_f32_16x16x32_bf16 v[22:25], v[166:169], v[190:193], v[22:25]
	v_mfma_f32_16x16x32_bf16 v[14:17], v[158:161], v[198:201], v[14:17]
	v_mfma_f32_16x16x32_bf16 v[2:5], v[166:169], v[198:201], v[2:5]
	v_mfma_f32_16x16x32_bf16 v[62:65], v[162:165], v[178:181], v[62:65]
	v_mfma_f32_16x16x32_bf16 v[54:57], v[170:173], v[178:181], v[54:57]
	v_mfma_f32_16x16x32_bf16 v[46:49], v[162:165], v[186:189], v[46:49]
	v_mfma_f32_16x16x32_bf16 v[38:41], v[170:173], v[186:189], v[38:41]
	v_mfma_f32_16x16x32_bf16 v[30:33], v[162:165], v[194:197], v[30:33]
	v_mfma_f32_16x16x32_bf16 v[22:25], v[170:173], v[194:197], v[22:25]
	v_mfma_f32_16x16x32_bf16 v[14:17], v[162:165], v[202:205], v[14:17]
	v_mfma_f32_16x16x32_bf16 v[2:5], v[170:173], v[202:205], v[2:5]
	s_barrier
	s_add_i32 s66, s66, 2
	s_add_u32 s64, s64, 0x100
	s_addc_u32 s65, s65, 0
	s_cmp_gt_u32 s66, 13
	s_mov_b64 s[36:37], s[0:1]
	s_cbranch_scc0 .LBB0_1424
	s_and_b64 vcc, exec, s[8:9]
	s_cbranch_vccz .LBB0_1427
	s_barrier
